# v40 + hand-written pipelined ph4 (ple layer 0) tile epilogue (same body as ph12's)
# baseline (speedup 1.0000x reference)
; __device__ __forceinline__ float bf_lo(unsigned w) { return __uint_as_float(w << 16); }
; __device__ __forceinline__ float bf_hi(unsigned w) { return __uint_as_float(w & 0xffff0000u); }
; __device__ __forceinline__ float sigmoidf_(float x) { return __builtin_amdgcn_rcpf(1.0f + __expf(-x)); }
; __device__ __forceinline__ float rinv_of(float ssq) { return rsqrtf(ssq * (1.0f / 1024.0f) + EPS); }
; __device__ __forceinline__ u32x4 pack8(const f32x4 a, const f32x4 b) { u32x4 w; w.x = cvt_pk_bf16(a[0], a[1]); w.y = cvt_pk_bf16(a[2], a[3]); w.z = cvt_pk_bf16(b[0], b[1]); w.w = cvt_pk_bf16(b[2], b[3]); return w; }
;     __device__ __forceinline__ void operator()(const AccT& acc, const pg8::Unit& u, int wr, int wc, int fr, int fq) const {
;     ...
; #pragma unroll
;                 for (int mm = 0; mm < 2; ++mm) { const int r = EPI_ROW(u, ai, 2 * mp + mm); rs[mm] = ssq_in[r];
; #pragma unroll
;                     for (int bj = 0; bj < 2; ++bj) { const int c = EPI_COL(u, bj); const float* hp = h + (size_t)r * D + c; hv[mm][bj][0] = *(const f32x4*)hp; hv[mm][bj][1] = *(const f32x4*)(hp + 4); pw[mm][bj] = *(const u32x4*)(pp + (size_t)r * D + c); } }
; #pragma unroll
;                 for (int mm = 0; mm < 2; ++mm) { const int m = 2 * mp + mm, r = EPI_ROW(u, ai, m); float s = 0.f; const float ri = rinv_of(rs[mm]);
; #pragma unroll
;                     for (int bj = 0; bj < 2; ++bj) { const int c = EPI_COL(u, bj); float* hp = h + (size_t)r * D + c; const u32x4 p4 = pw[mm][bj];
;                         const f32x4 a0 = acc[ai][bj][m][0] * ri, a1 = acc[ai][bj][m][1] * ri; f32x4 v0 = hv[mm][bj][0], v1 = hv[mm][bj][1];
;                         v0[0] += mul * sigmoidf_(a0[0]) * bf_lo(p4.x); v0[1] += mul * sigmoidf_(a0[1]) * bf_hi(p4.x); v0[2] += mul * sigmoidf_(a0[2]) * bf_lo(p4.y); v0[3] += mul * sigmoidf_(a0[3]) * bf_hi(p4.y);
;                         v1[0] += mul * sigmoidf_(a1[0]) * bf_lo(p4.z); v1[1] += mul * sigmoidf_(a1[1]) * bf_hi(p4.z); v1[2] += mul * sigmoidf_(a1[2]) * bf_lo(p4.w); v1[3] += mul * sigmoidf_(a1[3]) * bf_hi(p4.w);
;                         *(f32x4*)hp = v0; *(f32x4*)(hp + 4) = v1;
;                         if (hb) *(u32x4*)(hb + (size_t)r * D + c) = pack8(v0, v1);
;                         s += sq8(v0, v1); }
;                     ssq_commit(s, ssq, r, fq); }
.LBB0_1754:
	s_lshl_b32 s12, s34, 8
	s_lshl_b32 s13, s40, 6
	s_add_i32 s12, s12, s13
	v_add_u32_e32 v241, s12, v190
	s_lshl_b32 s12, s30, 8
	s_lshl_b32 s13, s45, 5
	s_add_i32 s12, s12, s13
	v_lshl_add_u32 v242, v191, 3, s12
	v_lshlrev_b32_e32 v243, 12, v241
	v_lshl_add_u32 v243, v242, 2, v243
	v_lshlrev_b32_e32 v226, 2, v241
	v_mov_b32_e32 v225, 0x358637bd
	v_mbcnt_lo_u32_b32 v224, -1, 0
	v_mbcnt_hi_u32_b32 v224, -1, v224
	v_lshlrev_b32_e32 v224, 2, v224
	v_cmp_eq_u32_e64 s[98:99], 0, v191
	v_mov_b32_e32 v232, v243
	v_lshrrev_b32_e32 v233, 1, v232
	global_load_dword v176, v226, s[14:15]
	global_load_dwordx4 v[128:131], v232, s[52:53]
	global_load_dwordx4 v[132:135], v232, s[52:53] offset:16
	global_load_dwordx4 v[136:139], v232, s[52:53] offset:512
	global_load_dwordx4 v[140:143], v232, s[52:53] offset:528
	global_load_dwordx4 v[144:147], v233, s[72:73]
	global_load_dwordx4 v[148:151], v233, s[72:73] offset:256
	v_add_u32_e32 v232, 0x10000, v243
	v_lshrrev_b32_e32 v233, 1, v232
	global_load_dword v177, v226, s[14:15] offset:64
	global_load_dwordx4 v[152:155], v232, s[52:53]
	global_load_dwordx4 v[156:159], v232, s[52:53] offset:16
	global_load_dwordx4 v[160:163], v232, s[52:53] offset:512
	global_load_dwordx4 v[164:167], v232, s[52:53] offset:528
	global_load_dwordx4 v[168:171], v233, s[72:73]
	global_load_dwordx4 v[172:175], v233, s[72:73] offset:256
	v_add_u32_e32 v232, 0x20000, v243
	v_lshrrev_b32_e32 v233, 1, v232
	global_load_dword v227, v226, s[14:15] offset:128
	global_load_dwordx4 v[178:181], v232, s[52:53]
	global_load_dwordx4 v[182:185], v232, s[52:53] offset:16
	global_load_dwordx4 v[186:189], v232, s[52:53] offset:512
	global_load_dwordx4 v[190:193], v232, s[52:53] offset:528
	global_load_dwordx4 v[212:215], v233, s[72:73]
	global_load_dwordx4 v[216:219], v233, s[72:73] offset:256
	v_add_u32_e32 v232, 0x30000, v243
	v_lshrrev_b32_e32 v233, 1, v232
	global_load_dword v228, v226, s[14:15] offset:192
	global_load_dwordx4 v[194:197], v232, s[52:53]
	global_load_dwordx4 v[198:201], v232, s[52:53] offset:16
	global_load_dwordx4 v[202:205], v232, s[52:53] offset:512
	global_load_dwordx4 v[206:209], v232, s[52:53] offset:528
	global_load_dwordx4 v[220:223], v233, s[72:73]
	global_load_dwordx4 v[244:247], v233, s[72:73] offset:256
	s_waitcnt vmcnt(21)
	v_fmamk_f32 v230, v176, 0x3a800000, v225
	v_rsq_f32_e32 v230, v230
	v_mov_b32_e32 v229, 0
	v_pk_mul_f32 v[236:237], v[124:125], v[230:231] op_sel_hi:[1,0]
	v_pk_mul_f32 v[238:239], v[126:127], v[230:231] op_sel_hi:[1,0]
	v_mul_f32_e32 v236, 0xbfb8aa3b, v236
	v_mul_f32_e32 v237, 0xbfb8aa3b, v237
	v_mul_f32_e32 v238, 0xbfb8aa3b, v238
	v_mul_f32_e32 v239, 0xbfb8aa3b, v239
	v_exp_f32_e32 v236, v236
	v_exp_f32_e32 v237, v237
	v_exp_f32_e32 v238, v238
	v_exp_f32_e32 v239, v239
	v_add_f32_e32 v236, 1.0, v236
	v_add_f32_e32 v237, 1.0, v237
	v_add_f32_e32 v238, 1.0, v238
	v_add_f32_e32 v239, 1.0, v239
	v_rcp_f32_e32 v236, v236
	v_rcp_f32_e32 v237, v237
	v_rcp_f32_e32 v238, v238
	v_rcp_f32_e32 v239, v239
	v_lshlrev_b32_e32 v232, 16, v144
	v_and_b32_e32 v233, 0xffff0000, v144
	v_lshlrev_b32_e32 v234, 16, v145
	v_and_b32_e32 v235, 0xffff0000, v145
	v_pk_fma_f32 v[124:125], v[236:237], v[232:233], v[128:129]
	v_pk_fma_f32 v[126:127], v[238:239], v[234:235], v[130:131]
	v_pk_mul_f32 v[236:237], v[124:125], v[124:125]
	v_pk_mul_f32 v[238:239], v[126:127], v[126:127]
	v_add_f32_e32 v229, v229, v236
	v_add_f32_e32 v229, v229, v237
	v_add_f32_e32 v229, v229, v238
	v_add_f32_e32 v229, v229, v239
	v_pk_mul_f32 v[236:237], v[120:121], v[230:231] op_sel_hi:[1,0]
	v_pk_mul_f32 v[238:239], v[122:123], v[230:231] op_sel_hi:[1,0]
	v_mul_f32_e32 v236, 0xbfb8aa3b, v236
	v_mul_f32_e32 v237, 0xbfb8aa3b, v237
	v_mul_f32_e32 v238, 0xbfb8aa3b, v238
	v_mul_f32_e32 v239, 0xbfb8aa3b, v239
	v_exp_f32_e32 v236, v236
	v_exp_f32_e32 v237, v237
	v_exp_f32_e32 v238, v238
	v_exp_f32_e32 v239, v239
	v_add_f32_e32 v236, 1.0, v236
	v_add_f32_e32 v237, 1.0, v237
	v_add_f32_e32 v238, 1.0, v238
	v_add_f32_e32 v239, 1.0, v239
	v_rcp_f32_e32 v236, v236
	v_rcp_f32_e32 v237, v237
	v_rcp_f32_e32 v238, v238
	v_rcp_f32_e32 v239, v239
	v_lshlrev_b32_e32 v232, 16, v146
	v_and_b32_e32 v233, 0xffff0000, v146
	v_lshlrev_b32_e32 v234, 16, v147
	v_and_b32_e32 v235, 0xffff0000, v147
	v_pk_fma_f32 v[120:121], v[236:237], v[232:233], v[132:133]
	v_pk_fma_f32 v[122:123], v[238:239], v[234:235], v[134:135]
	v_pk_mul_f32 v[236:237], v[120:121], v[120:121]
	v_pk_mul_f32 v[238:239], v[122:123], v[122:123]
	v_add_f32_e32 v229, v229, v236
	v_add_f32_e32 v229, v229, v237
	v_add_f32_e32 v229, v229, v238
	v_add_f32_e32 v229, v229, v239
	v_pk_mul_f32 v[236:237], v[116:117], v[230:231] op_sel_hi:[1,0]
	v_pk_mul_f32 v[238:239], v[118:119], v[230:231] op_sel_hi:[1,0]
	v_mul_f32_e32 v236, 0xbfb8aa3b, v236
	v_mul_f32_e32 v237, 0xbfb8aa3b, v237
	v_mul_f32_e32 v238, 0xbfb8aa3b, v238
	v_mul_f32_e32 v239, 0xbfb8aa3b, v239
	v_exp_f32_e32 v236, v236
	v_exp_f32_e32 v237, v237
	v_exp_f32_e32 v238, v238
	v_exp_f32_e32 v239, v239
	v_add_f32_e32 v236, 1.0, v236
	v_add_f32_e32 v237, 1.0, v237
	v_add_f32_e32 v238, 1.0, v238
	v_add_f32_e32 v239, 1.0, v239
	v_rcp_f32_e32 v236, v236
	v_rcp_f32_e32 v237, v237
	v_rcp_f32_e32 v238, v238
	v_rcp_f32_e32 v239, v239
	v_lshlrev_b32_e32 v232, 16, v148
	v_and_b32_e32 v233, 0xffff0000, v148
	v_lshlrev_b32_e32 v234, 16, v149
	v_and_b32_e32 v235, 0xffff0000, v149
	v_pk_fma_f32 v[116:117], v[236:237], v[232:233], v[136:137]
	v_pk_fma_f32 v[118:119], v[238:239], v[234:235], v[138:139]
	v_pk_mul_f32 v[236:237], v[116:117], v[116:117]
	v_pk_mul_f32 v[238:239], v[118:119], v[118:119]
	v_add_f32_e32 v229, v229, v236
	v_add_f32_e32 v229, v229, v237
; __device__ __forceinline__ float bf_lo(unsigned w) { return __uint_as_float(w << 16); }
; __device__ __forceinline__ float bf_hi(unsigned w) { return __uint_as_float(w & 0xffff0000u); }
; __device__ __forceinline__ float sigmoidf_(float x) { return __builtin_amdgcn_rcpf(1.0f + __expf(-x)); }
; __device__ __forceinline__ float rinv_of(float ssq) { return rsqrtf(ssq * (1.0f / 1024.0f) + EPS); }
; __device__ __forceinline__ u32x4 pack8(const f32x4 a, const f32x4 b) { u32x4 w; w.x = cvt_pk_bf16(a[0], a[1]); w.y = cvt_pk_bf16(a[2], a[3]); w.z = cvt_pk_bf16(b[0], b[1]); w.w = cvt_pk_bf16(b[2], b[3]); return w; }
; __device__ __forceinline__ float sq8(const f32x4 a, const f32x4 b) { return (a[0] * a[0] + a[1] * a[1]) + (a[2] * a[2] + a[3] * a[3]) + (b[0] * b[0] + b[1] * b[1]) + (b[2] * b[2] + b[3] * b[3]); }
; __device__ __forceinline__ void ssq_commit(float s, float* ssq, int r, int fq) { s += __shfl_xor(s, 16); s += __shfl_xor(s, 32); if (fq == 0) atomicAdd(ssq + r, s); }
;     __device__ __forceinline__ void operator()(const AccT& acc, const pg8::Unit& u, int wr, int wc, int fr, int fq) const {
;     ...
;                 for (int mm = 0; mm < 2; ++mm) { const int m = 2 * mp + mm, r = EPI_ROW(u, ai, m); float s = 0.f; const float ri = rinv_of(rs[mm]);
; #pragma unroll
;                     for (int bj = 0; bj < 2; ++bj) { const int c = EPI_COL(u, bj); float* hp = h + (size_t)r * D + c; const u32x4 p4 = pw[mm][bj];
;                         const f32x4 a0 = acc[ai][bj][m][0] * ri, a1 = acc[ai][bj][m][1] * ri; f32x4 v0 = hv[mm][bj][0], v1 = hv[mm][bj][1];
;                         v0[0] += mul * sigmoidf_(a0[0]) * bf_lo(p4.x); v0[1] += mul * sigmoidf_(a0[1]) * bf_hi(p4.x); v0[2] += mul * sigmoidf_(a0[2]) * bf_lo(p4.y); v0[3] += mul * sigmoidf_(a0[3]) * bf_hi(p4.y);
;                         v1[0] += mul * sigmoidf_(a1[0]) * bf_lo(p4.z); v1[1] += mul * sigmoidf_(a1[1]) * bf_hi(p4.z); v1[2] += mul * sigmoidf_(a1[2]) * bf_lo(p4.w); v1[3] += mul * sigmoidf_(a1[3]) * bf_hi(p4.w);
;                         *(f32x4*)hp = v0; *(f32x4*)(hp + 4) = v1;
;                         if (hb) *(u32x4*)(hb + (size_t)r * D + c) = pack8(v0, v1);
;                         s += sq8(v0, v1); }
;                     ssq_commit(s, ssq, r, fq); }
	v_add_f32_e32 v229, v229, v238
	v_add_f32_e32 v229, v229, v239
	v_pk_mul_f32 v[236:237], v[112:113], v[230:231] op_sel_hi:[1,0]
	v_pk_mul_f32 v[238:239], v[114:115], v[230:231] op_sel_hi:[1,0]
	v_mul_f32_e32 v236, 0xbfb8aa3b, v236
	v_mul_f32_e32 v237, 0xbfb8aa3b, v237
	v_mul_f32_e32 v238, 0xbfb8aa3b, v238
	v_mul_f32_e32 v239, 0xbfb8aa3b, v239
	v_exp_f32_e32 v236, v236
	v_exp_f32_e32 v237, v237
	v_exp_f32_e32 v238, v238
	v_exp_f32_e32 v239, v239
	v_add_f32_e32 v236, 1.0, v236
	v_add_f32_e32 v237, 1.0, v237
	v_add_f32_e32 v238, 1.0, v238
	v_add_f32_e32 v239, 1.0, v239
	v_rcp_f32_e32 v236, v236
	v_rcp_f32_e32 v237, v237
	v_rcp_f32_e32 v238, v238
	v_rcp_f32_e32 v239, v239
	v_lshlrev_b32_e32 v232, 16, v150
	v_and_b32_e32 v233, 0xffff0000, v150
	v_lshlrev_b32_e32 v234, 16, v151
	v_and_b32_e32 v235, 0xffff0000, v151
	v_pk_fma_f32 v[112:113], v[236:237], v[232:233], v[140:141]
	v_pk_fma_f32 v[114:115], v[238:239], v[234:235], v[142:143]
	v_pk_mul_f32 v[236:237], v[112:113], v[112:113]
	v_pk_mul_f32 v[238:239], v[114:115], v[114:115]
	v_add_f32_e32 v229, v229, v236
	v_add_f32_e32 v229, v229, v237
	v_add_f32_e32 v229, v229, v238
	v_add_f32_e32 v229, v229, v239
	v_mov_b32_e32 v232, v243
	v_lshrrev_b32_e32 v233, 1, v232
	v_cvt_pk_bf16_f32 v144, v124, v125
	v_cvt_pk_bf16_f32 v145, v126, v127
	v_cvt_pk_bf16_f32 v146, v120, v121
	v_cvt_pk_bf16_f32 v147, v122, v123
	v_cvt_pk_bf16_f32 v148, v116, v117
	v_cvt_pk_bf16_f32 v149, v118, v119
	v_cvt_pk_bf16_f32 v150, v112, v113
	v_cvt_pk_bf16_f32 v151, v114, v115
	global_store_dwordx4 v232, v[124:127], s[52:53]
	global_store_dwordx4 v232, v[120:123], s[52:53] offset:16
	global_store_dwordx4 v232, v[116:119], s[52:53] offset:512
	global_store_dwordx4 v232, v[112:115], s[52:53] offset:528
	global_store_dwordx4 v233, v[144:147], s[70:71]
	global_store_dwordx4 v233, v[148:151], s[70:71] offset:256
	v_xor_b32_e32 v232, 64, v224
	ds_bpermute_b32 v233, v232, v229
	s_waitcnt lgkmcnt(0)
	v_add_f32_e32 v229, v229, v233
	v_xor_b32_e32 v232, 0x80, v224
	ds_bpermute_b32 v233, v232, v229
	s_waitcnt lgkmcnt(0)
	v_add_f32_e32 v229, v229, v233
	s_and_saveexec_b64 s[100:101], s[98:99]
	global_atomic_add_f32 v226, v229, s[16:17]
	s_mov_b64 exec, s[100:101]
	s_waitcnt vmcnt(21)
	v_fmamk_f32 v230, v177, 0x3a800000, v225
	v_rsq_f32_e32 v230, v230
	v_mov_b32_e32 v229, 0
	v_pk_mul_f32 v[236:237], v[108:109], v[230:231] op_sel_hi:[1,0]
	v_pk_mul_f32 v[238:239], v[110:111], v[230:231] op_sel_hi:[1,0]
	v_mul_f32_e32 v236, 0xbfb8aa3b, v236
	v_mul_f32_e32 v237, 0xbfb8aa3b, v237
	v_mul_f32_e32 v238, 0xbfb8aa3b, v238
	v_mul_f32_e32 v239, 0xbfb8aa3b, v239
	v_exp_f32_e32 v236, v236
	v_exp_f32_e32 v237, v237
	v_exp_f32_e32 v238, v238
	v_exp_f32_e32 v239, v239
	v_add_f32_e32 v236, 1.0, v236
	v_add_f32_e32 v237, 1.0, v237
	v_add_f32_e32 v238, 1.0, v238
	v_add_f32_e32 v239, 1.0, v239
	v_rcp_f32_e32 v236, v236
	v_rcp_f32_e32 v237, v237
	v_rcp_f32_e32 v238, v238
	v_rcp_f32_e32 v239, v239
	v_lshlrev_b32_e32 v232, 16, v168
	v_and_b32_e32 v233, 0xffff0000, v168
	v_lshlrev_b32_e32 v234, 16, v169
	v_and_b32_e32 v235, 0xffff0000, v169
	v_pk_fma_f32 v[108:109], v[236:237], v[232:233], v[152:153]
	v_pk_fma_f32 v[110:111], v[238:239], v[234:235], v[154:155]
	v_pk_mul_f32 v[236:237], v[108:109], v[108:109]
	v_pk_mul_f32 v[238:239], v[110:111], v[110:111]
	v_add_f32_e32 v229, v229, v236
	v_add_f32_e32 v229, v229, v237
	v_add_f32_e32 v229, v229, v238
	v_add_f32_e32 v229, v229, v239
	v_pk_mul_f32 v[236:237], v[104:105], v[230:231] op_sel_hi:[1,0]
	v_pk_mul_f32 v[238:239], v[106:107], v[230:231] op_sel_hi:[1,0]
	v_mul_f32_e32 v236, 0xbfb8aa3b, v236
	v_mul_f32_e32 v237, 0xbfb8aa3b, v237
	v_mul_f32_e32 v238, 0xbfb8aa3b, v238
	v_mul_f32_e32 v239, 0xbfb8aa3b, v239
	v_exp_f32_e32 v236, v236
	v_exp_f32_e32 v237, v237
	v_exp_f32_e32 v238, v238
	v_exp_f32_e32 v239, v239
	v_add_f32_e32 v236, 1.0, v236
	v_add_f32_e32 v237, 1.0, v237
	v_add_f32_e32 v238, 1.0, v238
	v_add_f32_e32 v239, 1.0, v239
	v_rcp_f32_e32 v236, v236
	v_rcp_f32_e32 v237, v237
	v_rcp_f32_e32 v238, v238
	v_rcp_f32_e32 v239, v239
	v_lshlrev_b32_e32 v232, 16, v170
	v_and_b32_e32 v233, 0xffff0000, v170
	v_lshlrev_b32_e32 v234, 16, v171
	v_and_b32_e32 v235, 0xffff0000, v171
	v_pk_fma_f32 v[104:105], v[236:237], v[232:233], v[156:157]
	v_pk_fma_f32 v[106:107], v[238:239], v[234:235], v[158:159]
	v_pk_mul_f32 v[236:237], v[104:105], v[104:105]
	v_pk_mul_f32 v[238:239], v[106:107], v[106:107]
	v_add_f32_e32 v229, v229, v236
	v_add_f32_e32 v229, v229, v237
	v_add_f32_e32 v229, v229, v238
	v_add_f32_e32 v229, v229, v239
	v_pk_mul_f32 v[236:237], v[100:101], v[230:231] op_sel_hi:[1,0]
	v_pk_mul_f32 v[238:239], v[102:103], v[230:231] op_sel_hi:[1,0]
	v_mul_f32_e32 v236, 0xbfb8aa3b, v236
	v_mul_f32_e32 v237, 0xbfb8aa3b, v237
	v_mul_f32_e32 v238, 0xbfb8aa3b, v238
	v_mul_f32_e32 v239, 0xbfb8aa3b, v239
	v_exp_f32_e32 v236, v236
	v_exp_f32_e32 v237, v237
	v_exp_f32_e32 v238, v238
	v_exp_f32_e32 v239, v239
	v_add_f32_e32 v236, 1.0, v236
	v_add_f32_e32 v237, 1.0, v237
	v_add_f32_e32 v238, 1.0, v238
	v_add_f32_e32 v239, 1.0, v239
	v_rcp_f32_e32 v236, v236
	v_rcp_f32_e32 v237, v237
	v_rcp_f32_e32 v238, v238
	v_rcp_f32_e32 v239, v239
	v_lshlrev_b32_e32 v232, 16, v172
	v_and_b32_e32 v233, 0xffff0000, v172
	v_lshlrev_b32_e32 v234, 16, v173
	v_and_b32_e32 v235, 0xffff0000, v173
	v_pk_fma_f32 v[100:101], v[236:237], v[232:233], v[160:161]
	v_pk_fma_f32 v[102:103], v[238:239], v[234:235], v[162:163]
	v_pk_mul_f32 v[236:237], v[100:101], v[100:101]
	v_pk_mul_f32 v[238:239], v[102:103], v[102:103]
	v_add_f32_e32 v229, v229, v236
	v_add_f32_e32 v229, v229, v237
	v_add_f32_e32 v229, v229, v238
	v_add_f32_e32 v229, v229, v239
; __device__ __forceinline__ float bf_lo(unsigned w) { return __uint_as_float(w << 16); }
; __device__ __forceinline__ float bf_hi(unsigned w) { return __uint_as_float(w & 0xffff0000u); }
; __device__ __forceinline__ float sigmoidf_(float x) { return __builtin_amdgcn_rcpf(1.0f + __expf(-x)); }
; __device__ __forceinline__ float rinv_of(float ssq) { return rsqrtf(ssq * (1.0f / 1024.0f) + EPS); }
; __device__ __forceinline__ u32x4 pack8(const f32x4 a, const f32x4 b) { u32x4 w; w.x = cvt_pk_bf16(a[0], a[1]); w.y = cvt_pk_bf16(a[2], a[3]); w.z = cvt_pk_bf16(b[0], b[1]); w.w = cvt_pk_bf16(b[2], b[3]); return w; }
; __device__ __forceinline__ float sq8(const f32x4 a, const f32x4 b) { return (a[0] * a[0] + a[1] * a[1]) + (a[2] * a[2] + a[3] * a[3]) + (b[0] * b[0] + b[1] * b[1]) + (b[2] * b[2] + b[3] * b[3]); }
; __device__ __forceinline__ void ssq_commit(float s, float* ssq, int r, int fq) { s += __shfl_xor(s, 16); s += __shfl_xor(s, 32); if (fq == 0) atomicAdd(ssq + r, s); }
;     __device__ __forceinline__ void operator()(const AccT& acc, const pg8::Unit& u, int wr, int wc, int fr, int fq) const {
;     ...
;                 for (int mm = 0; mm < 2; ++mm) { const int m = 2 * mp + mm, r = EPI_ROW(u, ai, m); float s = 0.f; const float ri = rinv_of(rs[mm]);
; #pragma unroll
;                     for (int bj = 0; bj < 2; ++bj) { const int c = EPI_COL(u, bj); float* hp = h + (size_t)r * D + c; const u32x4 p4 = pw[mm][bj];
;                         const f32x4 a0 = acc[ai][bj][m][0] * ri, a1 = acc[ai][bj][m][1] * ri; f32x4 v0 = hv[mm][bj][0], v1 = hv[mm][bj][1];
;                         v0[0] += mul * sigmoidf_(a0[0]) * bf_lo(p4.x); v0[1] += mul * sigmoidf_(a0[1]) * bf_hi(p4.x); v0[2] += mul * sigmoidf_(a0[2]) * bf_lo(p4.y); v0[3] += mul * sigmoidf_(a0[3]) * bf_hi(p4.y);
;                         v1[0] += mul * sigmoidf_(a1[0]) * bf_lo(p4.z); v1[1] += mul * sigmoidf_(a1[1]) * bf_hi(p4.z); v1[2] += mul * sigmoidf_(a1[2]) * bf_lo(p4.w); v1[3] += mul * sigmoidf_(a1[3]) * bf_hi(p4.w);
;                         *(f32x4*)hp = v0; *(f32x4*)(hp + 4) = v1;
;                         if (hb) *(u32x4*)(hb + (size_t)r * D + c) = pack8(v0, v1);
;                         s += sq8(v0, v1); }
;                     ssq_commit(s, ssq, r, fq); }
	v_pk_mul_f32 v[236:237], v[96:97], v[230:231] op_sel_hi:[1,0]
	v_pk_mul_f32 v[238:239], v[98:99], v[230:231] op_sel_hi:[1,0]
	v_mul_f32_e32 v236, 0xbfb8aa3b, v236
	v_mul_f32_e32 v237, 0xbfb8aa3b, v237
	v_mul_f32_e32 v238, 0xbfb8aa3b, v238
	v_mul_f32_e32 v239, 0xbfb8aa3b, v239
	v_exp_f32_e32 v236, v236
	v_exp_f32_e32 v237, v237
	v_exp_f32_e32 v238, v238
	v_exp_f32_e32 v239, v239
	v_add_f32_e32 v236, 1.0, v236
	v_add_f32_e32 v237, 1.0, v237
	v_add_f32_e32 v238, 1.0, v238
	v_add_f32_e32 v239, 1.0, v239
	v_rcp_f32_e32 v236, v236
	v_rcp_f32_e32 v237, v237
	v_rcp_f32_e32 v238, v238
	v_rcp_f32_e32 v239, v239
	v_lshlrev_b32_e32 v232, 16, v174
	v_and_b32_e32 v233, 0xffff0000, v174
	v_lshlrev_b32_e32 v234, 16, v175
	v_and_b32_e32 v235, 0xffff0000, v175
	v_pk_fma_f32 v[96:97], v[236:237], v[232:233], v[164:165]
	v_pk_fma_f32 v[98:99], v[238:239], v[234:235], v[166:167]
	v_pk_mul_f32 v[236:237], v[96:97], v[96:97]
	v_pk_mul_f32 v[238:239], v[98:99], v[98:99]
	v_add_f32_e32 v229, v229, v236
	v_add_f32_e32 v229, v229, v237
	v_add_f32_e32 v229, v229, v238
	v_add_f32_e32 v229, v229, v239
	v_add_u32_e32 v232, 0x10000, v243
	v_lshrrev_b32_e32 v233, 1, v232
	v_cvt_pk_bf16_f32 v168, v108, v109
	v_cvt_pk_bf16_f32 v169, v110, v111
	v_cvt_pk_bf16_f32 v170, v104, v105
	v_cvt_pk_bf16_f32 v171, v106, v107
	v_cvt_pk_bf16_f32 v172, v100, v101
	v_cvt_pk_bf16_f32 v173, v102, v103
	v_cvt_pk_bf16_f32 v174, v96, v97
	v_cvt_pk_bf16_f32 v175, v98, v99
	global_store_dwordx4 v232, v[108:111], s[52:53]
	global_store_dwordx4 v232, v[104:107], s[52:53] offset:16
	global_store_dwordx4 v232, v[100:103], s[52:53] offset:512
	global_store_dwordx4 v232, v[96:99], s[52:53] offset:528
	global_store_dwordx4 v233, v[168:171], s[70:71]
	global_store_dwordx4 v233, v[172:175], s[70:71] offset:256
	v_xor_b32_e32 v232, 64, v224
	ds_bpermute_b32 v233, v232, v229
	s_waitcnt lgkmcnt(0)
	v_add_f32_e32 v229, v229, v233
	v_xor_b32_e32 v232, 0x80, v224
	ds_bpermute_b32 v233, v232, v229
	s_waitcnt lgkmcnt(0)
	v_add_f32_e32 v229, v229, v233
	s_and_saveexec_b64 s[100:101], s[98:99]
	global_atomic_add_f32 v226, v229, s[16:17] offset:64
	s_mov_b64 exec, s[100:101]
	v_add_u32_e32 v232, 0x80000, v243
	v_lshrrev_b32_e32 v233, 1, v232
	global_load_dword v176, v226, s[14:15] offset:512
	global_load_dwordx4 v[128:131], v232, s[52:53]
	global_load_dwordx4 v[132:135], v232, s[52:53] offset:16
	global_load_dwordx4 v[136:139], v232, s[52:53] offset:512
	global_load_dwordx4 v[140:143], v232, s[52:53] offset:528
	global_load_dwordx4 v[144:147], v233, s[72:73]
	global_load_dwordx4 v[148:151], v233, s[72:73] offset:256
	v_add_u32_e32 v232, 0x90000, v243
	v_lshrrev_b32_e32 v233, 1, v232
	global_load_dword v177, v226, s[14:15] offset:576
	global_load_dwordx4 v[152:155], v232, s[52:53]
	global_load_dwordx4 v[156:159], v232, s[52:53] offset:16
	global_load_dwordx4 v[160:163], v232, s[52:53] offset:512
	global_load_dwordx4 v[164:167], v232, s[52:53] offset:528
	global_load_dwordx4 v[168:171], v233, s[72:73]
	global_load_dwordx4 v[172:175], v233, s[72:73] offset:256
	s_waitcnt vmcnt(35)
	v_fmamk_f32 v230, v227, 0x3a800000, v225
	v_rsq_f32_e32 v230, v230
	v_mov_b32_e32 v229, 0
	v_pk_mul_f32 v[236:237], v[92:93], v[230:231] op_sel_hi:[1,0]
	v_pk_mul_f32 v[238:239], v[94:95], v[230:231] op_sel_hi:[1,0]
	v_mul_f32_e32 v236, 0xbfb8aa3b, v236
	v_mul_f32_e32 v237, 0xbfb8aa3b, v237
	v_mul_f32_e32 v238, 0xbfb8aa3b, v238
	v_mul_f32_e32 v239, 0xbfb8aa3b, v239
	v_exp_f32_e32 v236, v236
	v_exp_f32_e32 v237, v237
	v_exp_f32_e32 v238, v238
	v_exp_f32_e32 v239, v239
	v_add_f32_e32 v236, 1.0, v236
	v_add_f32_e32 v237, 1.0, v237
	v_add_f32_e32 v238, 1.0, v238
	v_add_f32_e32 v239, 1.0, v239
	v_rcp_f32_e32 v236, v236
	v_rcp_f32_e32 v237, v237
	v_rcp_f32_e32 v238, v238
	v_rcp_f32_e32 v239, v239
	v_lshlrev_b32_e32 v232, 16, v212
	v_and_b32_e32 v233, 0xffff0000, v212
	v_lshlrev_b32_e32 v234, 16, v213
	v_and_b32_e32 v235, 0xffff0000, v213
	v_pk_fma_f32 v[92:93], v[236:237], v[232:233], v[178:179]
	v_pk_fma_f32 v[94:95], v[238:239], v[234:235], v[180:181]
	v_pk_mul_f32 v[236:237], v[92:93], v[92:93]
	v_pk_mul_f32 v[238:239], v[94:95], v[94:95]
	v_add_f32_e32 v229, v229, v236
	v_add_f32_e32 v229, v229, v237
	v_add_f32_e32 v229, v229, v238
	v_add_f32_e32 v229, v229, v239
	v_pk_mul_f32 v[236:237], v[88:89], v[230:231] op_sel_hi:[1,0]
	v_pk_mul_f32 v[238:239], v[90:91], v[230:231] op_sel_hi:[1,0]
	v_mul_f32_e32 v236, 0xbfb8aa3b, v236
	v_mul_f32_e32 v237, 0xbfb8aa3b, v237
	v_mul_f32_e32 v238, 0xbfb8aa3b, v238
	v_mul_f32_e32 v239, 0xbfb8aa3b, v239
	v_exp_f32_e32 v236, v236
	v_exp_f32_e32 v237, v237
	v_exp_f32_e32 v238, v238
	v_exp_f32_e32 v239, v239
	v_add_f32_e32 v236, 1.0, v236
	v_add_f32_e32 v237, 1.0, v237
	v_add_f32_e32 v238, 1.0, v238
	v_add_f32_e32 v239, 1.0, v239
	v_rcp_f32_e32 v236, v236
	v_rcp_f32_e32 v237, v237
	v_rcp_f32_e32 v238, v238
	v_rcp_f32_e32 v239, v239
	v_lshlrev_b32_e32 v232, 16, v214
	v_and_b32_e32 v233, 0xffff0000, v214
	v_lshlrev_b32_e32 v234, 16, v215
	v_and_b32_e32 v235, 0xffff0000, v215
	v_pk_fma_f32 v[88:89], v[236:237], v[232:233], v[182:183]
	v_pk_fma_f32 v[90:91], v[238:239], v[234:235], v[184:185]
	v_pk_mul_f32 v[236:237], v[88:89], v[88:89]
	v_pk_mul_f32 v[238:239], v[90:91], v[90:91]
	v_add_f32_e32 v229, v229, v236
	v_add_f32_e32 v229, v229, v237
	v_add_f32_e32 v229, v229, v238
	v_add_f32_e32 v229, v229, v239
	v_pk_mul_f32 v[236:237], v[84:85], v[230:231] op_sel_hi:[1,0]
	v_pk_mul_f32 v[238:239], v[86:87], v[230:231] op_sel_hi:[1,0]
	v_mul_f32_e32 v236, 0xbfb8aa3b, v236
	v_mul_f32_e32 v237, 0xbfb8aa3b, v237
	v_mul_f32_e32 v238, 0xbfb8aa3b, v238
	v_mul_f32_e32 v239, 0xbfb8aa3b, v239
	v_exp_f32_e32 v236, v236
; __device__ __forceinline__ float bf_lo(unsigned w) { return __uint_as_float(w << 16); }
; __device__ __forceinline__ float bf_hi(unsigned w) { return __uint_as_float(w & 0xffff0000u); }
; __device__ __forceinline__ float sigmoidf_(float x) { return __builtin_amdgcn_rcpf(1.0f + __expf(-x)); }
; __device__ __forceinline__ float rinv_of(float ssq) { return rsqrtf(ssq * (1.0f / 1024.0f) + EPS); }
; __device__ __forceinline__ u32x4 pack8(const f32x4 a, const f32x4 b) { u32x4 w; w.x = cvt_pk_bf16(a[0], a[1]); w.y = cvt_pk_bf16(a[2], a[3]); w.z = cvt_pk_bf16(b[0], b[1]); w.w = cvt_pk_bf16(b[2], b[3]); return w; }
; __device__ __forceinline__ float sq8(const f32x4 a, const f32x4 b) { return (a[0] * a[0] + a[1] * a[1]) + (a[2] * a[2] + a[3] * a[3]) + (b[0] * b[0] + b[1] * b[1]) + (b[2] * b[2] + b[3] * b[3]); }
; __device__ __forceinline__ void ssq_commit(float s, float* ssq, int r, int fq) { s += __shfl_xor(s, 16); s += __shfl_xor(s, 32); if (fq == 0) atomicAdd(ssq + r, s); }
;     __device__ __forceinline__ void operator()(const AccT& acc, const pg8::Unit& u, int wr, int wc, int fr, int fq) const {
;     ...
;                 for (int mm = 0; mm < 2; ++mm) { const int m = 2 * mp + mm, r = EPI_ROW(u, ai, m); float s = 0.f; const float ri = rinv_of(rs[mm]);
; #pragma unroll
;                     for (int bj = 0; bj < 2; ++bj) { const int c = EPI_COL(u, bj); float* hp = h + (size_t)r * D + c; const u32x4 p4 = pw[mm][bj];
;                         const f32x4 a0 = acc[ai][bj][m][0] * ri, a1 = acc[ai][bj][m][1] * ri; f32x4 v0 = hv[mm][bj][0], v1 = hv[mm][bj][1];
;                         v0[0] += mul * sigmoidf_(a0[0]) * bf_lo(p4.x); v0[1] += mul * sigmoidf_(a0[1]) * bf_hi(p4.x); v0[2] += mul * sigmoidf_(a0[2]) * bf_lo(p4.y); v0[3] += mul * sigmoidf_(a0[3]) * bf_hi(p4.y);
;                         v1[0] += mul * sigmoidf_(a1[0]) * bf_lo(p4.z); v1[1] += mul * sigmoidf_(a1[1]) * bf_hi(p4.z); v1[2] += mul * sigmoidf_(a1[2]) * bf_lo(p4.w); v1[3] += mul * sigmoidf_(a1[3]) * bf_hi(p4.w);
;                         *(f32x4*)hp = v0; *(f32x4*)(hp + 4) = v1;
;                         if (hb) *(u32x4*)(hb + (size_t)r * D + c) = pack8(v0, v1);
;                         s += sq8(v0, v1); }
;                     ssq_commit(s, ssq, r, fq); }
	v_exp_f32_e32 v237, v237
	v_exp_f32_e32 v238, v238
	v_exp_f32_e32 v239, v239
	v_add_f32_e32 v236, 1.0, v236
	v_add_f32_e32 v237, 1.0, v237
	v_add_f32_e32 v238, 1.0, v238
	v_add_f32_e32 v239, 1.0, v239
	v_rcp_f32_e32 v236, v236
	v_rcp_f32_e32 v237, v237
	v_rcp_f32_e32 v238, v238
	v_rcp_f32_e32 v239, v239
	v_lshlrev_b32_e32 v232, 16, v216
	v_and_b32_e32 v233, 0xffff0000, v216
	v_lshlrev_b32_e32 v234, 16, v217
	v_and_b32_e32 v235, 0xffff0000, v217
	v_pk_fma_f32 v[84:85], v[236:237], v[232:233], v[186:187]
	v_pk_fma_f32 v[86:87], v[238:239], v[234:235], v[188:189]
	v_pk_mul_f32 v[236:237], v[84:85], v[84:85]
	v_pk_mul_f32 v[238:239], v[86:87], v[86:87]
	v_add_f32_e32 v229, v229, v236
	v_add_f32_e32 v229, v229, v237
	v_add_f32_e32 v229, v229, v238
	v_add_f32_e32 v229, v229, v239
	v_pk_mul_f32 v[236:237], v[80:81], v[230:231] op_sel_hi:[1,0]
	v_pk_mul_f32 v[238:239], v[82:83], v[230:231] op_sel_hi:[1,0]
	v_mul_f32_e32 v236, 0xbfb8aa3b, v236
	v_mul_f32_e32 v237, 0xbfb8aa3b, v237
	v_mul_f32_e32 v238, 0xbfb8aa3b, v238
	v_mul_f32_e32 v239, 0xbfb8aa3b, v239
	v_exp_f32_e32 v236, v236
	v_exp_f32_e32 v237, v237
	v_exp_f32_e32 v238, v238
	v_exp_f32_e32 v239, v239
	v_add_f32_e32 v236, 1.0, v236
	v_add_f32_e32 v237, 1.0, v237
	v_add_f32_e32 v238, 1.0, v238
	v_add_f32_e32 v239, 1.0, v239
	v_rcp_f32_e32 v236, v236
	v_rcp_f32_e32 v237, v237
	v_rcp_f32_e32 v238, v238
	v_rcp_f32_e32 v239, v239
	v_lshlrev_b32_e32 v232, 16, v218
	v_and_b32_e32 v233, 0xffff0000, v218
	v_lshlrev_b32_e32 v234, 16, v219
	v_and_b32_e32 v235, 0xffff0000, v219
	v_pk_fma_f32 v[80:81], v[236:237], v[232:233], v[190:191]
	v_pk_fma_f32 v[82:83], v[238:239], v[234:235], v[192:193]
	v_pk_mul_f32 v[236:237], v[80:81], v[80:81]
	v_pk_mul_f32 v[238:239], v[82:83], v[82:83]
	v_add_f32_e32 v229, v229, v236
	v_add_f32_e32 v229, v229, v237
	v_add_f32_e32 v229, v229, v238
	v_add_f32_e32 v229, v229, v239
	v_add_u32_e32 v232, 0x20000, v243
	v_lshrrev_b32_e32 v233, 1, v232
	v_cvt_pk_bf16_f32 v212, v92, v93
	v_cvt_pk_bf16_f32 v213, v94, v95
	v_cvt_pk_bf16_f32 v214, v88, v89
	v_cvt_pk_bf16_f32 v215, v90, v91
	v_cvt_pk_bf16_f32 v216, v84, v85
	v_cvt_pk_bf16_f32 v217, v86, v87
	v_cvt_pk_bf16_f32 v218, v80, v81
	v_cvt_pk_bf16_f32 v219, v82, v83
	global_store_dwordx4 v232, v[92:95], s[52:53]
	global_store_dwordx4 v232, v[88:91], s[52:53] offset:16
	global_store_dwordx4 v232, v[84:87], s[52:53] offset:512
	global_store_dwordx4 v232, v[80:83], s[52:53] offset:528
	global_store_dwordx4 v233, v[212:215], s[70:71]
	global_store_dwordx4 v233, v[216:219], s[70:71] offset:256
	v_xor_b32_e32 v232, 64, v224
	ds_bpermute_b32 v233, v232, v229
	s_waitcnt lgkmcnt(0)
	v_add_f32_e32 v229, v229, v233
	v_xor_b32_e32 v232, 0x80, v224
	ds_bpermute_b32 v233, v232, v229
	s_waitcnt lgkmcnt(0)
	v_add_f32_e32 v229, v229, v233
	s_and_saveexec_b64 s[100:101], s[98:99]
	global_atomic_add_f32 v226, v229, s[16:17] offset:128
	s_mov_b64 exec, s[100:101]
	s_waitcnt vmcnt(35)
	v_fmamk_f32 v230, v228, 0x3a800000, v225
	v_rsq_f32_e32 v230, v230
	v_mov_b32_e32 v229, 0
	v_pk_mul_f32 v[236:237], v[76:77], v[230:231] op_sel_hi:[1,0]
	v_pk_mul_f32 v[238:239], v[78:79], v[230:231] op_sel_hi:[1,0]
	v_mul_f32_e32 v236, 0xbfb8aa3b, v236
	v_mul_f32_e32 v237, 0xbfb8aa3b, v237
	v_mul_f32_e32 v238, 0xbfb8aa3b, v238
	v_mul_f32_e32 v239, 0xbfb8aa3b, v239
	v_exp_f32_e32 v236, v236
	v_exp_f32_e32 v237, v237
	v_exp_f32_e32 v238, v238
	v_exp_f32_e32 v239, v239
	v_add_f32_e32 v236, 1.0, v236
	v_add_f32_e32 v237, 1.0, v237
	v_add_f32_e32 v238, 1.0, v238
	v_add_f32_e32 v239, 1.0, v239
	v_rcp_f32_e32 v236, v236
	v_rcp_f32_e32 v237, v237
	v_rcp_f32_e32 v238, v238
	v_rcp_f32_e32 v239, v239
	v_lshlrev_b32_e32 v232, 16, v220
	v_and_b32_e32 v233, 0xffff0000, v220
	v_lshlrev_b32_e32 v234, 16, v221
	v_and_b32_e32 v235, 0xffff0000, v221
	v_pk_fma_f32 v[76:77], v[236:237], v[232:233], v[194:195]
	v_pk_fma_f32 v[78:79], v[238:239], v[234:235], v[196:197]
	v_pk_mul_f32 v[236:237], v[76:77], v[76:77]
	v_pk_mul_f32 v[238:239], v[78:79], v[78:79]
	v_add_f32_e32 v229, v229, v236
	v_add_f32_e32 v229, v229, v237
	v_add_f32_e32 v229, v229, v238
	v_add_f32_e32 v229, v229, v239
	v_pk_mul_f32 v[236:237], v[72:73], v[230:231] op_sel_hi:[1,0]
	v_pk_mul_f32 v[238:239], v[74:75], v[230:231] op_sel_hi:[1,0]
	v_mul_f32_e32 v236, 0xbfb8aa3b, v236
	v_mul_f32_e32 v237, 0xbfb8aa3b, v237
	v_mul_f32_e32 v238, 0xbfb8aa3b, v238
	v_mul_f32_e32 v239, 0xbfb8aa3b, v239
	v_exp_f32_e32 v236, v236
	v_exp_f32_e32 v237, v237
	v_exp_f32_e32 v238, v238
	v_exp_f32_e32 v239, v239
	v_add_f32_e32 v236, 1.0, v236
	v_add_f32_e32 v237, 1.0, v237
	v_add_f32_e32 v238, 1.0, v238
	v_add_f32_e32 v239, 1.0, v239
	v_rcp_f32_e32 v236, v236
	v_rcp_f32_e32 v237, v237
	v_rcp_f32_e32 v238, v238
	v_rcp_f32_e32 v239, v239
	v_lshlrev_b32_e32 v232, 16, v222
	v_and_b32_e32 v233, 0xffff0000, v222
	v_lshlrev_b32_e32 v234, 16, v223
	v_and_b32_e32 v235, 0xffff0000, v223
	v_pk_fma_f32 v[72:73], v[236:237], v[232:233], v[198:199]
	v_pk_fma_f32 v[74:75], v[238:239], v[234:235], v[200:201]
	v_pk_mul_f32 v[236:237], v[72:73], v[72:73]
	v_pk_mul_f32 v[238:239], v[74:75], v[74:75]
	v_add_f32_e32 v229, v229, v236
	v_add_f32_e32 v229, v229, v237
	v_add_f32_e32 v229, v229, v238
	v_add_f32_e32 v229, v229, v239
	v_pk_mul_f32 v[236:237], v[68:69], v[230:231] op_sel_hi:[1,0]
	v_pk_mul_f32 v[238:239], v[70:71], v[230:231] op_sel_hi:[1,0]
	v_mul_f32_e32 v236, 0xbfb8aa3b, v236
	v_mul_f32_e32 v237, 0xbfb8aa3b, v237
	v_mul_f32_e32 v238, 0xbfb8aa3b, v238
	v_mul_f32_e32 v239, 0xbfb8aa3b, v239
	v_exp_f32_e32 v236, v236
	v_exp_f32_e32 v237, v237
	v_exp_f32_e32 v238, v238
	v_exp_f32_e32 v239, v239
	v_add_f32_e32 v236, 1.0, v236
	v_add_f32_e32 v237, 1.0, v237
; __device__ __forceinline__ float bf_lo(unsigned w) { return __uint_as_float(w << 16); }
; __device__ __forceinline__ float bf_hi(unsigned w) { return __uint_as_float(w & 0xffff0000u); }
; __device__ __forceinline__ float sigmoidf_(float x) { return __builtin_amdgcn_rcpf(1.0f + __expf(-x)); }
; __device__ __forceinline__ float rinv_of(float ssq) { return rsqrtf(ssq * (1.0f / 1024.0f) + EPS); }
; __device__ __forceinline__ u32x4 pack8(const f32x4 a, const f32x4 b) { u32x4 w; w.x = cvt_pk_bf16(a[0], a[1]); w.y = cvt_pk_bf16(a[2], a[3]); w.z = cvt_pk_bf16(b[0], b[1]); w.w = cvt_pk_bf16(b[2], b[3]); return w; }
; __device__ __forceinline__ float sq8(const f32x4 a, const f32x4 b) { return (a[0] * a[0] + a[1] * a[1]) + (a[2] * a[2] + a[3] * a[3]) + (b[0] * b[0] + b[1] * b[1]) + (b[2] * b[2] + b[3] * b[3]); }
; __device__ __forceinline__ void ssq_commit(float s, float* ssq, int r, int fq) { s += __shfl_xor(s, 16); s += __shfl_xor(s, 32); if (fq == 0) atomicAdd(ssq + r, s); }
;     __device__ __forceinline__ void operator()(const AccT& acc, const pg8::Unit& u, int wr, int wc, int fr, int fq) const {
;     ...
;                 for (int mm = 0; mm < 2; ++mm) { const int m = 2 * mp + mm, r = EPI_ROW(u, ai, m); float s = 0.f; const float ri = rinv_of(rs[mm]);
; #pragma unroll
;                     for (int bj = 0; bj < 2; ++bj) { const int c = EPI_COL(u, bj); float* hp = h + (size_t)r * D + c; const u32x4 p4 = pw[mm][bj];
;                         const f32x4 a0 = acc[ai][bj][m][0] * ri, a1 = acc[ai][bj][m][1] * ri; f32x4 v0 = hv[mm][bj][0], v1 = hv[mm][bj][1];
;                         v0[0] += mul * sigmoidf_(a0[0]) * bf_lo(p4.x); v0[1] += mul * sigmoidf_(a0[1]) * bf_hi(p4.x); v0[2] += mul * sigmoidf_(a0[2]) * bf_lo(p4.y); v0[3] += mul * sigmoidf_(a0[3]) * bf_hi(p4.y);
;                         v1[0] += mul * sigmoidf_(a1[0]) * bf_lo(p4.z); v1[1] += mul * sigmoidf_(a1[1]) * bf_hi(p4.z); v1[2] += mul * sigmoidf_(a1[2]) * bf_lo(p4.w); v1[3] += mul * sigmoidf_(a1[3]) * bf_hi(p4.w);
;                         *(f32x4*)hp = v0; *(f32x4*)(hp + 4) = v1;
;                         if (hb) *(u32x4*)(hb + (size_t)r * D + c) = pack8(v0, v1);
;                         s += sq8(v0, v1); }
;                     ssq_commit(s, ssq, r, fq); }
	v_add_f32_e32 v238, 1.0, v238
	v_add_f32_e32 v239, 1.0, v239
	v_rcp_f32_e32 v236, v236
	v_rcp_f32_e32 v237, v237
	v_rcp_f32_e32 v238, v238
	v_rcp_f32_e32 v239, v239
	v_lshlrev_b32_e32 v232, 16, v244
	v_and_b32_e32 v233, 0xffff0000, v244
	v_lshlrev_b32_e32 v234, 16, v245
	v_and_b32_e32 v235, 0xffff0000, v245
	v_pk_fma_f32 v[68:69], v[236:237], v[232:233], v[202:203]
	v_pk_fma_f32 v[70:71], v[238:239], v[234:235], v[204:205]
	v_pk_mul_f32 v[236:237], v[68:69], v[68:69]
	v_pk_mul_f32 v[238:239], v[70:71], v[70:71]
	v_add_f32_e32 v229, v229, v236
	v_add_f32_e32 v229, v229, v237
	v_add_f32_e32 v229, v229, v238
	v_add_f32_e32 v229, v229, v239
	v_pk_mul_f32 v[236:237], v[64:65], v[230:231] op_sel_hi:[1,0]
	v_pk_mul_f32 v[238:239], v[66:67], v[230:231] op_sel_hi:[1,0]
	v_mul_f32_e32 v236, 0xbfb8aa3b, v236
	v_mul_f32_e32 v237, 0xbfb8aa3b, v237
	v_mul_f32_e32 v238, 0xbfb8aa3b, v238
	v_mul_f32_e32 v239, 0xbfb8aa3b, v239
	v_exp_f32_e32 v236, v236
	v_exp_f32_e32 v237, v237
	v_exp_f32_e32 v238, v238
	v_exp_f32_e32 v239, v239
	v_add_f32_e32 v236, 1.0, v236
	v_add_f32_e32 v237, 1.0, v237
	v_add_f32_e32 v238, 1.0, v238
	v_add_f32_e32 v239, 1.0, v239
	v_rcp_f32_e32 v236, v236
	v_rcp_f32_e32 v237, v237
	v_rcp_f32_e32 v238, v238
	v_rcp_f32_e32 v239, v239
	v_lshlrev_b32_e32 v232, 16, v246
	v_and_b32_e32 v233, 0xffff0000, v246
	v_lshlrev_b32_e32 v234, 16, v247
	v_and_b32_e32 v235, 0xffff0000, v247
	v_pk_fma_f32 v[64:65], v[236:237], v[232:233], v[206:207]
	v_pk_fma_f32 v[66:67], v[238:239], v[234:235], v[208:209]
	v_pk_mul_f32 v[236:237], v[64:65], v[64:65]
	v_pk_mul_f32 v[238:239], v[66:67], v[66:67]
	v_add_f32_e32 v229, v229, v236
	v_add_f32_e32 v229, v229, v237
	v_add_f32_e32 v229, v229, v238
	v_add_f32_e32 v229, v229, v239
	v_add_u32_e32 v232, 0x30000, v243
	v_lshrrev_b32_e32 v233, 1, v232
	v_cvt_pk_bf16_f32 v220, v76, v77
	v_cvt_pk_bf16_f32 v221, v78, v79
	v_cvt_pk_bf16_f32 v222, v72, v73
	v_cvt_pk_bf16_f32 v223, v74, v75
	v_cvt_pk_bf16_f32 v244, v68, v69
	v_cvt_pk_bf16_f32 v245, v70, v71
	v_cvt_pk_bf16_f32 v246, v64, v65
	v_cvt_pk_bf16_f32 v247, v66, v67
	global_store_dwordx4 v232, v[76:79], s[52:53]
	global_store_dwordx4 v232, v[72:75], s[52:53] offset:16
	global_store_dwordx4 v232, v[68:71], s[52:53] offset:512
	global_store_dwordx4 v232, v[64:67], s[52:53] offset:528
	global_store_dwordx4 v233, v[220:223], s[70:71]
	global_store_dwordx4 v233, v[244:247], s[70:71] offset:256
	v_xor_b32_e32 v232, 64, v224
	ds_bpermute_b32 v233, v232, v229
	s_waitcnt lgkmcnt(0)
	v_add_f32_e32 v229, v229, v233
	v_xor_b32_e32 v232, 0x80, v224
	ds_bpermute_b32 v233, v232, v229
	s_waitcnt lgkmcnt(0)
	v_add_f32_e32 v229, v229, v233
	s_and_saveexec_b64 s[100:101], s[98:99]
	global_atomic_add_f32 v226, v229, s[16:17] offset:192
	s_mov_b64 exec, s[100:101]
	v_add_u32_e32 v232, 0xa0000, v243
	v_lshrrev_b32_e32 v233, 1, v232
	global_load_dword v227, v226, s[14:15] offset:640
	global_load_dwordx4 v[178:181], v232, s[52:53]
	global_load_dwordx4 v[182:185], v232, s[52:53] offset:16
	global_load_dwordx4 v[186:189], v232, s[52:53] offset:512
	global_load_dwordx4 v[190:193], v232, s[52:53] offset:528
	global_load_dwordx4 v[212:215], v233, s[72:73]
	global_load_dwordx4 v[216:219], v233, s[72:73] offset:256
	v_add_u32_e32 v232, 0xb0000, v243
	v_lshrrev_b32_e32 v233, 1, v232
	global_load_dword v228, v226, s[14:15] offset:704
	global_load_dwordx4 v[194:197], v232, s[52:53]
	global_load_dwordx4 v[198:201], v232, s[52:53] offset:16
	global_load_dwordx4 v[202:205], v232, s[52:53] offset:512
	global_load_dwordx4 v[206:209], v232, s[52:53] offset:528
	global_load_dwordx4 v[220:223], v233, s[72:73]
	global_load_dwordx4 v[244:247], v233, s[72:73] offset:256
	s_waitcnt vmcnt(35)
	v_fmamk_f32 v230, v176, 0x3a800000, v225
	v_rsq_f32_e32 v230, v230
	v_mov_b32_e32 v229, 0
	v_pk_mul_f32 v[236:237], v[60:61], v[230:231] op_sel_hi:[1,0]
	v_pk_mul_f32 v[238:239], v[62:63], v[230:231] op_sel_hi:[1,0]
	v_mul_f32_e32 v236, 0xbfb8aa3b, v236
	v_mul_f32_e32 v237, 0xbfb8aa3b, v237
	v_mul_f32_e32 v238, 0xbfb8aa3b, v238
	v_mul_f32_e32 v239, 0xbfb8aa3b, v239
	v_exp_f32_e32 v236, v236
	v_exp_f32_e32 v237, v237
	v_exp_f32_e32 v238, v238
	v_exp_f32_e32 v239, v239
	v_add_f32_e32 v236, 1.0, v236
	v_add_f32_e32 v237, 1.0, v237
	v_add_f32_e32 v238, 1.0, v238
	v_add_f32_e32 v239, 1.0, v239
	v_rcp_f32_e32 v236, v236
	v_rcp_f32_e32 v237, v237
	v_rcp_f32_e32 v238, v238
	v_rcp_f32_e32 v239, v239
	v_lshlrev_b32_e32 v232, 16, v144
	v_and_b32_e32 v233, 0xffff0000, v144
	v_lshlrev_b32_e32 v234, 16, v145
	v_and_b32_e32 v235, 0xffff0000, v145
	v_pk_fma_f32 v[60:61], v[236:237], v[232:233], v[128:129]
	v_pk_fma_f32 v[62:63], v[238:239], v[234:235], v[130:131]
	v_pk_mul_f32 v[236:237], v[60:61], v[60:61]
	v_pk_mul_f32 v[238:239], v[62:63], v[62:63]
	v_add_f32_e32 v229, v229, v236
	v_add_f32_e32 v229, v229, v237
	v_add_f32_e32 v229, v229, v238
	v_add_f32_e32 v229, v229, v239
	v_pk_mul_f32 v[236:237], v[56:57], v[230:231] op_sel_hi:[1,0]
	v_pk_mul_f32 v[238:239], v[58:59], v[230:231] op_sel_hi:[1,0]
	v_mul_f32_e32 v236, 0xbfb8aa3b, v236
	v_mul_f32_e32 v237, 0xbfb8aa3b, v237
	v_mul_f32_e32 v238, 0xbfb8aa3b, v238
	v_mul_f32_e32 v239, 0xbfb8aa3b, v239
	v_exp_f32_e32 v236, v236
	v_exp_f32_e32 v237, v237
	v_exp_f32_e32 v238, v238
	v_exp_f32_e32 v239, v239
	v_add_f32_e32 v236, 1.0, v236
	v_add_f32_e32 v237, 1.0, v237
	v_add_f32_e32 v238, 1.0, v238
	v_add_f32_e32 v239, 1.0, v239
	v_rcp_f32_e32 v236, v236
	v_rcp_f32_e32 v237, v237
	v_rcp_f32_e32 v238, v238
	v_rcp_f32_e32 v239, v239
	v_lshlrev_b32_e32 v232, 16, v146
	v_and_b32_e32 v233, 0xffff0000, v146
	v_lshlrev_b32_e32 v234, 16, v147
	v_and_b32_e32 v235, 0xffff0000, v147
; __device__ __forceinline__ float bf_lo(unsigned w) { return __uint_as_float(w << 16); }
; __device__ __forceinline__ float bf_hi(unsigned w) { return __uint_as_float(w & 0xffff0000u); }
; __device__ __forceinline__ float sigmoidf_(float x) { return __builtin_amdgcn_rcpf(1.0f + __expf(-x)); }
; __device__ __forceinline__ float rinv_of(float ssq) { return rsqrtf(ssq * (1.0f / 1024.0f) + EPS); }
; __device__ __forceinline__ u32x4 pack8(const f32x4 a, const f32x4 b) { u32x4 w; w.x = cvt_pk_bf16(a[0], a[1]); w.y = cvt_pk_bf16(a[2], a[3]); w.z = cvt_pk_bf16(b[0], b[1]); w.w = cvt_pk_bf16(b[2], b[3]); return w; }
; __device__ __forceinline__ float sq8(const f32x4 a, const f32x4 b) { return (a[0] * a[0] + a[1] * a[1]) + (a[2] * a[2] + a[3] * a[3]) + (b[0] * b[0] + b[1] * b[1]) + (b[2] * b[2] + b[3] * b[3]); }
; __device__ __forceinline__ void ssq_commit(float s, float* ssq, int r, int fq) { s += __shfl_xor(s, 16); s += __shfl_xor(s, 32); if (fq == 0) atomicAdd(ssq + r, s); }
;     __device__ __forceinline__ void operator()(const AccT& acc, const pg8::Unit& u, int wr, int wc, int fr, int fq) const {
;     ...
;                 for (int mm = 0; mm < 2; ++mm) { const int m = 2 * mp + mm, r = EPI_ROW(u, ai, m); float s = 0.f; const float ri = rinv_of(rs[mm]);
; #pragma unroll
;                     for (int bj = 0; bj < 2; ++bj) { const int c = EPI_COL(u, bj); float* hp = h + (size_t)r * D + c; const u32x4 p4 = pw[mm][bj];
;                         const f32x4 a0 = acc[ai][bj][m][0] * ri, a1 = acc[ai][bj][m][1] * ri; f32x4 v0 = hv[mm][bj][0], v1 = hv[mm][bj][1];
;                         v0[0] += mul * sigmoidf_(a0[0]) * bf_lo(p4.x); v0[1] += mul * sigmoidf_(a0[1]) * bf_hi(p4.x); v0[2] += mul * sigmoidf_(a0[2]) * bf_lo(p4.y); v0[3] += mul * sigmoidf_(a0[3]) * bf_hi(p4.y);
;                         v1[0] += mul * sigmoidf_(a1[0]) * bf_lo(p4.z); v1[1] += mul * sigmoidf_(a1[1]) * bf_hi(p4.z); v1[2] += mul * sigmoidf_(a1[2]) * bf_lo(p4.w); v1[3] += mul * sigmoidf_(a1[3]) * bf_hi(p4.w);
;                         *(f32x4*)hp = v0; *(f32x4*)(hp + 4) = v1;
;                         if (hb) *(u32x4*)(hb + (size_t)r * D + c) = pack8(v0, v1);
;                         s += sq8(v0, v1); }
;                     ssq_commit(s, ssq, r, fq); }
	v_pk_fma_f32 v[56:57], v[236:237], v[232:233], v[132:133]
	v_pk_fma_f32 v[58:59], v[238:239], v[234:235], v[134:135]
	v_pk_mul_f32 v[236:237], v[56:57], v[56:57]
	v_pk_mul_f32 v[238:239], v[58:59], v[58:59]
	v_add_f32_e32 v229, v229, v236
	v_add_f32_e32 v229, v229, v237
	v_add_f32_e32 v229, v229, v238
	v_add_f32_e32 v229, v229, v239
	v_pk_mul_f32 v[236:237], v[52:53], v[230:231] op_sel_hi:[1,0]
	v_pk_mul_f32 v[238:239], v[54:55], v[230:231] op_sel_hi:[1,0]
	v_mul_f32_e32 v236, 0xbfb8aa3b, v236
	v_mul_f32_e32 v237, 0xbfb8aa3b, v237
	v_mul_f32_e32 v238, 0xbfb8aa3b, v238
	v_mul_f32_e32 v239, 0xbfb8aa3b, v239
	v_exp_f32_e32 v236, v236
	v_exp_f32_e32 v237, v237
	v_exp_f32_e32 v238, v238
	v_exp_f32_e32 v239, v239
	v_add_f32_e32 v236, 1.0, v236
	v_add_f32_e32 v237, 1.0, v237
	v_add_f32_e32 v238, 1.0, v238
	v_add_f32_e32 v239, 1.0, v239
	v_rcp_f32_e32 v236, v236
	v_rcp_f32_e32 v237, v237
	v_rcp_f32_e32 v238, v238
	v_rcp_f32_e32 v239, v239
	v_lshlrev_b32_e32 v232, 16, v148
	v_and_b32_e32 v233, 0xffff0000, v148
	v_lshlrev_b32_e32 v234, 16, v149
	v_and_b32_e32 v235, 0xffff0000, v149
	v_pk_fma_f32 v[52:53], v[236:237], v[232:233], v[136:137]
	v_pk_fma_f32 v[54:55], v[238:239], v[234:235], v[138:139]
	v_pk_mul_f32 v[236:237], v[52:53], v[52:53]
	v_pk_mul_f32 v[238:239], v[54:55], v[54:55]
	v_add_f32_e32 v229, v229, v236
	v_add_f32_e32 v229, v229, v237
	v_add_f32_e32 v229, v229, v238
	v_add_f32_e32 v229, v229, v239
	v_pk_mul_f32 v[236:237], v[48:49], v[230:231] op_sel_hi:[1,0]
	v_pk_mul_f32 v[238:239], v[50:51], v[230:231] op_sel_hi:[1,0]
	v_mul_f32_e32 v236, 0xbfb8aa3b, v236
	v_mul_f32_e32 v237, 0xbfb8aa3b, v237
	v_mul_f32_e32 v238, 0xbfb8aa3b, v238
	v_mul_f32_e32 v239, 0xbfb8aa3b, v239
	v_exp_f32_e32 v236, v236
	v_exp_f32_e32 v237, v237
	v_exp_f32_e32 v238, v238
	v_exp_f32_e32 v239, v239
	v_add_f32_e32 v236, 1.0, v236
	v_add_f32_e32 v237, 1.0, v237
	v_add_f32_e32 v238, 1.0, v238
	v_add_f32_e32 v239, 1.0, v239
	v_rcp_f32_e32 v236, v236
	v_rcp_f32_e32 v237, v237
	v_rcp_f32_e32 v238, v238
	v_rcp_f32_e32 v239, v239
	v_lshlrev_b32_e32 v232, 16, v150
	v_and_b32_e32 v233, 0xffff0000, v150
	v_lshlrev_b32_e32 v234, 16, v151
	v_and_b32_e32 v235, 0xffff0000, v151
	v_pk_fma_f32 v[48:49], v[236:237], v[232:233], v[140:141]
	v_pk_fma_f32 v[50:51], v[238:239], v[234:235], v[142:143]
	v_pk_mul_f32 v[236:237], v[48:49], v[48:49]
	v_pk_mul_f32 v[238:239], v[50:51], v[50:51]
	v_add_f32_e32 v229, v229, v236
	v_add_f32_e32 v229, v229, v237
	v_add_f32_e32 v229, v229, v238
	v_add_f32_e32 v229, v229, v239
	v_add_u32_e32 v232, 0x80000, v243
	v_lshrrev_b32_e32 v233, 1, v232
	v_cvt_pk_bf16_f32 v144, v60, v61
	v_cvt_pk_bf16_f32 v145, v62, v63
	v_cvt_pk_bf16_f32 v146, v56, v57
	v_cvt_pk_bf16_f32 v147, v58, v59
	v_cvt_pk_bf16_f32 v148, v52, v53
	v_cvt_pk_bf16_f32 v149, v54, v55
	v_cvt_pk_bf16_f32 v150, v48, v49
	v_cvt_pk_bf16_f32 v151, v50, v51
	global_store_dwordx4 v232, v[60:63], s[52:53]
	global_store_dwordx4 v232, v[56:59], s[52:53] offset:16
	global_store_dwordx4 v232, v[52:55], s[52:53] offset:512
	global_store_dwordx4 v232, v[48:51], s[52:53] offset:528
	global_store_dwordx4 v233, v[144:147], s[70:71]
	global_store_dwordx4 v233, v[148:151], s[70:71] offset:256
	v_xor_b32_e32 v232, 64, v224
	ds_bpermute_b32 v233, v232, v229
	s_waitcnt lgkmcnt(0)
	v_add_f32_e32 v229, v229, v233
	v_xor_b32_e32 v232, 0x80, v224
	ds_bpermute_b32 v233, v232, v229
	s_waitcnt lgkmcnt(0)
	v_add_f32_e32 v229, v229, v233
	s_and_saveexec_b64 s[100:101], s[98:99]
	global_atomic_add_f32 v226, v229, s[16:17] offset:512
	s_mov_b64 exec, s[100:101]
	s_waitcnt vmcnt(35)
	v_fmamk_f32 v230, v177, 0x3a800000, v225
	v_rsq_f32_e32 v230, v230
	v_mov_b32_e32 v229, 0
	v_pk_mul_f32 v[236:237], v[44:45], v[230:231] op_sel_hi:[1,0]
	v_pk_mul_f32 v[238:239], v[46:47], v[230:231] op_sel_hi:[1,0]
	v_mul_f32_e32 v236, 0xbfb8aa3b, v236
	v_mul_f32_e32 v237, 0xbfb8aa3b, v237
	v_mul_f32_e32 v238, 0xbfb8aa3b, v238
	v_mul_f32_e32 v239, 0xbfb8aa3b, v239
	v_exp_f32_e32 v236, v236
	v_exp_f32_e32 v237, v237
	v_exp_f32_e32 v238, v238
	v_exp_f32_e32 v239, v239
	v_add_f32_e32 v236, 1.0, v236
	v_add_f32_e32 v237, 1.0, v237
	v_add_f32_e32 v238, 1.0, v238
	v_add_f32_e32 v239, 1.0, v239
	v_rcp_f32_e32 v236, v236
	v_rcp_f32_e32 v237, v237
	v_rcp_f32_e32 v238, v238
	v_rcp_f32_e32 v239, v239
	v_lshlrev_b32_e32 v232, 16, v168
	v_and_b32_e32 v233, 0xffff0000, v168
	v_lshlrev_b32_e32 v234, 16, v169
	v_and_b32_e32 v235, 0xffff0000, v169
	v_pk_fma_f32 v[44:45], v[236:237], v[232:233], v[152:153]
	v_pk_fma_f32 v[46:47], v[238:239], v[234:235], v[154:155]
	v_pk_mul_f32 v[236:237], v[44:45], v[44:45]
	v_pk_mul_f32 v[238:239], v[46:47], v[46:47]
	v_add_f32_e32 v229, v229, v236
	v_add_f32_e32 v229, v229, v237
	v_add_f32_e32 v229, v229, v238
	v_add_f32_e32 v229, v229, v239
	v_pk_mul_f32 v[236:237], v[40:41], v[230:231] op_sel_hi:[1,0]
	v_pk_mul_f32 v[238:239], v[42:43], v[230:231] op_sel_hi:[1,0]
	v_mul_f32_e32 v236, 0xbfb8aa3b, v236
	v_mul_f32_e32 v237, 0xbfb8aa3b, v237
	v_mul_f32_e32 v238, 0xbfb8aa3b, v238
	v_mul_f32_e32 v239, 0xbfb8aa3b, v239
	v_exp_f32_e32 v236, v236
	v_exp_f32_e32 v237, v237
	v_exp_f32_e32 v238, v238
	v_exp_f32_e32 v239, v239
	v_add_f32_e32 v236, 1.0, v236
	v_add_f32_e32 v237, 1.0, v237
	v_add_f32_e32 v238, 1.0, v238
	v_add_f32_e32 v239, 1.0, v239
	v_rcp_f32_e32 v236, v236
	v_rcp_f32_e32 v237, v237
	v_rcp_f32_e32 v238, v238
	v_rcp_f32_e32 v239, v239
	v_lshlrev_b32_e32 v232, 16, v170
	v_and_b32_e32 v233, 0xffff0000, v170
	v_lshlrev_b32_e32 v234, 16, v171
	v_and_b32_e32 v235, 0xffff0000, v171
	v_pk_fma_f32 v[40:41], v[236:237], v[232:233], v[156:157]
	v_pk_fma_f32 v[42:43], v[238:239], v[234:235], v[158:159]
; __device__ __forceinline__ float bf_lo(unsigned w) { return __uint_as_float(w << 16); }
; __device__ __forceinline__ float bf_hi(unsigned w) { return __uint_as_float(w & 0xffff0000u); }
; __device__ __forceinline__ float sigmoidf_(float x) { return __builtin_amdgcn_rcpf(1.0f + __expf(-x)); }
; __device__ __forceinline__ float rinv_of(float ssq) { return rsqrtf(ssq * (1.0f / 1024.0f) + EPS); }
; __device__ __forceinline__ u32x4 pack8(const f32x4 a, const f32x4 b) { u32x4 w; w.x = cvt_pk_bf16(a[0], a[1]); w.y = cvt_pk_bf16(a[2], a[3]); w.z = cvt_pk_bf16(b[0], b[1]); w.w = cvt_pk_bf16(b[2], b[3]); return w; }
; __device__ __forceinline__ float sq8(const f32x4 a, const f32x4 b) { return (a[0] * a[0] + a[1] * a[1]) + (a[2] * a[2] + a[3] * a[3]) + (b[0] * b[0] + b[1] * b[1]) + (b[2] * b[2] + b[3] * b[3]); }
; __device__ __forceinline__ void ssq_commit(float s, float* ssq, int r, int fq) { s += __shfl_xor(s, 16); s += __shfl_xor(s, 32); if (fq == 0) atomicAdd(ssq + r, s); }
;     __device__ __forceinline__ void operator()(const AccT& acc, const pg8::Unit& u, int wr, int wc, int fr, int fq) const {
;     ...
;                 for (int mm = 0; mm < 2; ++mm) { const int m = 2 * mp + mm, r = EPI_ROW(u, ai, m); float s = 0.f; const float ri = rinv_of(rs[mm]);
; #pragma unroll
;                     for (int bj = 0; bj < 2; ++bj) { const int c = EPI_COL(u, bj); float* hp = h + (size_t)r * D + c; const u32x4 p4 = pw[mm][bj];
;                         const f32x4 a0 = acc[ai][bj][m][0] * ri, a1 = acc[ai][bj][m][1] * ri; f32x4 v0 = hv[mm][bj][0], v1 = hv[mm][bj][1];
;                         v0[0] += mul * sigmoidf_(a0[0]) * bf_lo(p4.x); v0[1] += mul * sigmoidf_(a0[1]) * bf_hi(p4.x); v0[2] += mul * sigmoidf_(a0[2]) * bf_lo(p4.y); v0[3] += mul * sigmoidf_(a0[3]) * bf_hi(p4.y);
;                         v1[0] += mul * sigmoidf_(a1[0]) * bf_lo(p4.z); v1[1] += mul * sigmoidf_(a1[1]) * bf_hi(p4.z); v1[2] += mul * sigmoidf_(a1[2]) * bf_lo(p4.w); v1[3] += mul * sigmoidf_(a1[3]) * bf_hi(p4.w);
;                         *(f32x4*)hp = v0; *(f32x4*)(hp + 4) = v1;
;                         if (hb) *(u32x4*)(hb + (size_t)r * D + c) = pack8(v0, v1);
;                         s += sq8(v0, v1); }
;                     ssq_commit(s, ssq, r, fq); }
	v_pk_mul_f32 v[236:237], v[40:41], v[40:41]
	v_pk_mul_f32 v[238:239], v[42:43], v[42:43]
	v_add_f32_e32 v229, v229, v236
	v_add_f32_e32 v229, v229, v237
	v_add_f32_e32 v229, v229, v238
	v_add_f32_e32 v229, v229, v239
	v_pk_mul_f32 v[236:237], v[36:37], v[230:231] op_sel_hi:[1,0]
	v_pk_mul_f32 v[238:239], v[38:39], v[230:231] op_sel_hi:[1,0]
	v_mul_f32_e32 v236, 0xbfb8aa3b, v236
	v_mul_f32_e32 v237, 0xbfb8aa3b, v237
	v_mul_f32_e32 v238, 0xbfb8aa3b, v238
	v_mul_f32_e32 v239, 0xbfb8aa3b, v239
	v_exp_f32_e32 v236, v236
	v_exp_f32_e32 v237, v237
	v_exp_f32_e32 v238, v238
	v_exp_f32_e32 v239, v239
	v_add_f32_e32 v236, 1.0, v236
	v_add_f32_e32 v237, 1.0, v237
	v_add_f32_e32 v238, 1.0, v238
	v_add_f32_e32 v239, 1.0, v239
	v_rcp_f32_e32 v236, v236
	v_rcp_f32_e32 v237, v237
	v_rcp_f32_e32 v238, v238
	v_rcp_f32_e32 v239, v239
	v_lshlrev_b32_e32 v232, 16, v172
	v_and_b32_e32 v233, 0xffff0000, v172
	v_lshlrev_b32_e32 v234, 16, v173
	v_and_b32_e32 v235, 0xffff0000, v173
	v_pk_fma_f32 v[36:37], v[236:237], v[232:233], v[160:161]
	v_pk_fma_f32 v[38:39], v[238:239], v[234:235], v[162:163]
	v_pk_mul_f32 v[236:237], v[36:37], v[36:37]
	v_pk_mul_f32 v[238:239], v[38:39], v[38:39]
	v_add_f32_e32 v229, v229, v236
	v_add_f32_e32 v229, v229, v237
	v_add_f32_e32 v229, v229, v238
	v_add_f32_e32 v229, v229, v239
	v_pk_mul_f32 v[236:237], v[32:33], v[230:231] op_sel_hi:[1,0]
	v_pk_mul_f32 v[238:239], v[34:35], v[230:231] op_sel_hi:[1,0]
	v_mul_f32_e32 v236, 0xbfb8aa3b, v236
	v_mul_f32_e32 v237, 0xbfb8aa3b, v237
	v_mul_f32_e32 v238, 0xbfb8aa3b, v238
	v_mul_f32_e32 v239, 0xbfb8aa3b, v239
	v_exp_f32_e32 v236, v236
	v_exp_f32_e32 v237, v237
	v_exp_f32_e32 v238, v238
	v_exp_f32_e32 v239, v239
	v_add_f32_e32 v236, 1.0, v236
	v_add_f32_e32 v237, 1.0, v237
	v_add_f32_e32 v238, 1.0, v238
	v_add_f32_e32 v239, 1.0, v239
	v_rcp_f32_e32 v236, v236
	v_rcp_f32_e32 v237, v237
	v_rcp_f32_e32 v238, v238
	v_rcp_f32_e32 v239, v239
	v_lshlrev_b32_e32 v232, 16, v174
	v_and_b32_e32 v233, 0xffff0000, v174
	v_lshlrev_b32_e32 v234, 16, v175
	v_and_b32_e32 v235, 0xffff0000, v175
	v_pk_fma_f32 v[32:33], v[236:237], v[232:233], v[164:165]
	v_pk_fma_f32 v[34:35], v[238:239], v[234:235], v[166:167]
	v_pk_mul_f32 v[236:237], v[32:33], v[32:33]
	v_pk_mul_f32 v[238:239], v[34:35], v[34:35]
	v_add_f32_e32 v229, v229, v236
	v_add_f32_e32 v229, v229, v237
	v_add_f32_e32 v229, v229, v238
	v_add_f32_e32 v229, v229, v239
	v_add_u32_e32 v232, 0x90000, v243
	v_lshrrev_b32_e32 v233, 1, v232
	v_cvt_pk_bf16_f32 v168, v44, v45
	v_cvt_pk_bf16_f32 v169, v46, v47
	v_cvt_pk_bf16_f32 v170, v40, v41
	v_cvt_pk_bf16_f32 v171, v42, v43
	v_cvt_pk_bf16_f32 v172, v36, v37
	v_cvt_pk_bf16_f32 v173, v38, v39
	v_cvt_pk_bf16_f32 v174, v32, v33
	v_cvt_pk_bf16_f32 v175, v34, v35
	global_store_dwordx4 v232, v[44:47], s[52:53]
	global_store_dwordx4 v232, v[40:43], s[52:53] offset:16
	global_store_dwordx4 v232, v[36:39], s[52:53] offset:512
	global_store_dwordx4 v232, v[32:35], s[52:53] offset:528
	global_store_dwordx4 v233, v[168:171], s[70:71]
	global_store_dwordx4 v233, v[172:175], s[70:71] offset:256
	v_xor_b32_e32 v232, 64, v224
	ds_bpermute_b32 v233, v232, v229
	s_waitcnt lgkmcnt(0)
	v_add_f32_e32 v229, v229, v233
	v_xor_b32_e32 v232, 0x80, v224
	ds_bpermute_b32 v233, v232, v229
	s_waitcnt lgkmcnt(0)
	v_add_f32_e32 v229, v229, v233
	s_and_saveexec_b64 s[100:101], s[98:99]
	global_atomic_add_f32 v226, v229, s[16:17] offset:576
	s_mov_b64 exec, s[100:101]
	s_waitcnt vmcnt(21)
	v_fmamk_f32 v230, v227, 0x3a800000, v225
	v_rsq_f32_e32 v230, v230
	v_mov_b32_e32 v229, 0
	v_pk_mul_f32 v[236:237], v[28:29], v[230:231] op_sel_hi:[1,0]
	v_pk_mul_f32 v[238:239], v[30:31], v[230:231] op_sel_hi:[1,0]
	v_mul_f32_e32 v236, 0xbfb8aa3b, v236
	v_mul_f32_e32 v237, 0xbfb8aa3b, v237
	v_mul_f32_e32 v238, 0xbfb8aa3b, v238
	v_mul_f32_e32 v239, 0xbfb8aa3b, v239
	v_exp_f32_e32 v236, v236
	v_exp_f32_e32 v237, v237
	v_exp_f32_e32 v238, v238
	v_exp_f32_e32 v239, v239
	v_add_f32_e32 v236, 1.0, v236
	v_add_f32_e32 v237, 1.0, v237
	v_add_f32_e32 v238, 1.0, v238
	v_add_f32_e32 v239, 1.0, v239
	v_rcp_f32_e32 v236, v236
	v_rcp_f32_e32 v237, v237
	v_rcp_f32_e32 v238, v238
	v_rcp_f32_e32 v239, v239
	v_lshlrev_b32_e32 v232, 16, v212
	v_and_b32_e32 v233, 0xffff0000, v212
	v_lshlrev_b32_e32 v234, 16, v213
	v_and_b32_e32 v235, 0xffff0000, v213
	v_pk_fma_f32 v[28:29], v[236:237], v[232:233], v[178:179]
	v_pk_fma_f32 v[30:31], v[238:239], v[234:235], v[180:181]
	v_pk_mul_f32 v[236:237], v[28:29], v[28:29]
	v_pk_mul_f32 v[238:239], v[30:31], v[30:31]
	v_add_f32_e32 v229, v229, v236
	v_add_f32_e32 v229, v229, v237
	v_add_f32_e32 v229, v229, v238
	v_add_f32_e32 v229, v229, v239
	v_pk_mul_f32 v[236:237], v[24:25], v[230:231] op_sel_hi:[1,0]
	v_pk_mul_f32 v[238:239], v[26:27], v[230:231] op_sel_hi:[1,0]
	v_mul_f32_e32 v236, 0xbfb8aa3b, v236
	v_mul_f32_e32 v237, 0xbfb8aa3b, v237
	v_mul_f32_e32 v238, 0xbfb8aa3b, v238
	v_mul_f32_e32 v239, 0xbfb8aa3b, v239
	v_exp_f32_e32 v236, v236
	v_exp_f32_e32 v237, v237
	v_exp_f32_e32 v238, v238
	v_exp_f32_e32 v239, v239
	v_add_f32_e32 v236, 1.0, v236
	v_add_f32_e32 v237, 1.0, v237
	v_add_f32_e32 v238, 1.0, v238
	v_add_f32_e32 v239, 1.0, v239
	v_rcp_f32_e32 v236, v236
	v_rcp_f32_e32 v237, v237
	v_rcp_f32_e32 v238, v238
	v_rcp_f32_e32 v239, v239
	v_lshlrev_b32_e32 v232, 16, v214
	v_and_b32_e32 v233, 0xffff0000, v214
	v_lshlrev_b32_e32 v234, 16, v215
	v_and_b32_e32 v235, 0xffff0000, v215
	v_pk_fma_f32 v[24:25], v[236:237], v[232:233], v[182:183]
	v_pk_fma_f32 v[26:27], v[238:239], v[234:235], v[184:185]
	v_pk_mul_f32 v[236:237], v[24:25], v[24:25]
	v_pk_mul_f32 v[238:239], v[26:27], v[26:27]
	v_add_f32_e32 v229, v229, v236
; __device__ __forceinline__ float bf_lo(unsigned w) { return __uint_as_float(w << 16); }
; __device__ __forceinline__ float bf_hi(unsigned w) { return __uint_as_float(w & 0xffff0000u); }
; __device__ __forceinline__ float sigmoidf_(float x) { return __builtin_amdgcn_rcpf(1.0f + __expf(-x)); }
; __device__ __forceinline__ float rinv_of(float ssq) { return rsqrtf(ssq * (1.0f / 1024.0f) + EPS); }
; __device__ __forceinline__ u32x4 pack8(const f32x4 a, const f32x4 b) { u32x4 w; w.x = cvt_pk_bf16(a[0], a[1]); w.y = cvt_pk_bf16(a[2], a[3]); w.z = cvt_pk_bf16(b[0], b[1]); w.w = cvt_pk_bf16(b[2], b[3]); return w; }
; __device__ __forceinline__ float sq8(const f32x4 a, const f32x4 b) { return (a[0] * a[0] + a[1] * a[1]) + (a[2] * a[2] + a[3] * a[3]) + (b[0] * b[0] + b[1] * b[1]) + (b[2] * b[2] + b[3] * b[3]); }
; __device__ __forceinline__ void ssq_commit(float s, float* ssq, int r, int fq) { s += __shfl_xor(s, 16); s += __shfl_xor(s, 32); if (fq == 0) atomicAdd(ssq + r, s); }
;     __device__ __forceinline__ void operator()(const AccT& acc, const pg8::Unit& u, int wr, int wc, int fr, int fq) const {
;     ...
;                 for (int mm = 0; mm < 2; ++mm) { const int m = 2 * mp + mm, r = EPI_ROW(u, ai, m); float s = 0.f; const float ri = rinv_of(rs[mm]);
; #pragma unroll
;                     for (int bj = 0; bj < 2; ++bj) { const int c = EPI_COL(u, bj); float* hp = h + (size_t)r * D + c; const u32x4 p4 = pw[mm][bj];
;                         const f32x4 a0 = acc[ai][bj][m][0] * ri, a1 = acc[ai][bj][m][1] * ri; f32x4 v0 = hv[mm][bj][0], v1 = hv[mm][bj][1];
;                         v0[0] += mul * sigmoidf_(a0[0]) * bf_lo(p4.x); v0[1] += mul * sigmoidf_(a0[1]) * bf_hi(p4.x); v0[2] += mul * sigmoidf_(a0[2]) * bf_lo(p4.y); v0[3] += mul * sigmoidf_(a0[3]) * bf_hi(p4.y);
;                         v1[0] += mul * sigmoidf_(a1[0]) * bf_lo(p4.z); v1[1] += mul * sigmoidf_(a1[1]) * bf_hi(p4.z); v1[2] += mul * sigmoidf_(a1[2]) * bf_lo(p4.w); v1[3] += mul * sigmoidf_(a1[3]) * bf_hi(p4.w);
;                         *(f32x4*)hp = v0; *(f32x4*)(hp + 4) = v1;
;                         if (hb) *(u32x4*)(hb + (size_t)r * D + c) = pack8(v0, v1);
;                         s += sq8(v0, v1); }
;                     ssq_commit(s, ssq, r, fq); }
	v_add_f32_e32 v229, v229, v237
	v_add_f32_e32 v229, v229, v238
	v_add_f32_e32 v229, v229, v239
	v_pk_mul_f32 v[236:237], v[20:21], v[230:231] op_sel_hi:[1,0]
	v_pk_mul_f32 v[238:239], v[22:23], v[230:231] op_sel_hi:[1,0]
	v_mul_f32_e32 v236, 0xbfb8aa3b, v236
	v_mul_f32_e32 v237, 0xbfb8aa3b, v237
	v_mul_f32_e32 v238, 0xbfb8aa3b, v238
	v_mul_f32_e32 v239, 0xbfb8aa3b, v239
	v_exp_f32_e32 v236, v236
	v_exp_f32_e32 v237, v237
	v_exp_f32_e32 v238, v238
	v_exp_f32_e32 v239, v239
	v_add_f32_e32 v236, 1.0, v236
	v_add_f32_e32 v237, 1.0, v237
	v_add_f32_e32 v238, 1.0, v238
	v_add_f32_e32 v239, 1.0, v239
	v_rcp_f32_e32 v236, v236
	v_rcp_f32_e32 v237, v237
	v_rcp_f32_e32 v238, v238
	v_rcp_f32_e32 v239, v239
	v_lshlrev_b32_e32 v232, 16, v216
	v_and_b32_e32 v233, 0xffff0000, v216
	v_lshlrev_b32_e32 v234, 16, v217
	v_and_b32_e32 v235, 0xffff0000, v217
	v_pk_fma_f32 v[20:21], v[236:237], v[232:233], v[186:187]
	v_pk_fma_f32 v[22:23], v[238:239], v[234:235], v[188:189]
	v_pk_mul_f32 v[236:237], v[20:21], v[20:21]
	v_pk_mul_f32 v[238:239], v[22:23], v[22:23]
	v_add_f32_e32 v229, v229, v236
	v_add_f32_e32 v229, v229, v237
	v_add_f32_e32 v229, v229, v238
	v_add_f32_e32 v229, v229, v239
	v_pk_mul_f32 v[236:237], v[16:17], v[230:231] op_sel_hi:[1,0]
	v_pk_mul_f32 v[238:239], v[18:19], v[230:231] op_sel_hi:[1,0]
	v_mul_f32_e32 v236, 0xbfb8aa3b, v236
	v_mul_f32_e32 v237, 0xbfb8aa3b, v237
	v_mul_f32_e32 v238, 0xbfb8aa3b, v238
	v_mul_f32_e32 v239, 0xbfb8aa3b, v239
	v_exp_f32_e32 v236, v236
	v_exp_f32_e32 v237, v237
	v_exp_f32_e32 v238, v238
	v_exp_f32_e32 v239, v239
	v_add_f32_e32 v236, 1.0, v236
	v_add_f32_e32 v237, 1.0, v237
	v_add_f32_e32 v238, 1.0, v238
	v_add_f32_e32 v239, 1.0, v239
	v_rcp_f32_e32 v236, v236
	v_rcp_f32_e32 v237, v237
	v_rcp_f32_e32 v238, v238
	v_rcp_f32_e32 v239, v239
	v_lshlrev_b32_e32 v232, 16, v218
	v_and_b32_e32 v233, 0xffff0000, v218
	v_lshlrev_b32_e32 v234, 16, v219
	v_and_b32_e32 v235, 0xffff0000, v219
	v_pk_fma_f32 v[16:17], v[236:237], v[232:233], v[190:191]
	v_pk_fma_f32 v[18:19], v[238:239], v[234:235], v[192:193]
	v_pk_mul_f32 v[236:237], v[16:17], v[16:17]
	v_pk_mul_f32 v[238:239], v[18:19], v[18:19]
	v_add_f32_e32 v229, v229, v236
	v_add_f32_e32 v229, v229, v237
	v_add_f32_e32 v229, v229, v238
	v_add_f32_e32 v229, v229, v239
	v_add_u32_e32 v232, 0xa0000, v243
	v_lshrrev_b32_e32 v233, 1, v232
	v_cvt_pk_bf16_f32 v212, v28, v29
	v_cvt_pk_bf16_f32 v213, v30, v31
	v_cvt_pk_bf16_f32 v214, v24, v25
	v_cvt_pk_bf16_f32 v215, v26, v27
	v_cvt_pk_bf16_f32 v216, v20, v21
	v_cvt_pk_bf16_f32 v217, v22, v23
	v_cvt_pk_bf16_f32 v218, v16, v17
	v_cvt_pk_bf16_f32 v219, v18, v19
	global_store_dwordx4 v232, v[28:31], s[52:53]
	global_store_dwordx4 v232, v[24:27], s[52:53] offset:16
	global_store_dwordx4 v232, v[20:23], s[52:53] offset:512
	global_store_dwordx4 v232, v[16:19], s[52:53] offset:528
	global_store_dwordx4 v233, v[212:215], s[70:71]
	global_store_dwordx4 v233, v[216:219], s[70:71] offset:256
	v_xor_b32_e32 v232, 64, v224
	ds_bpermute_b32 v233, v232, v229
	s_waitcnt lgkmcnt(0)
	v_add_f32_e32 v229, v229, v233
	v_xor_b32_e32 v232, 0x80, v224
	ds_bpermute_b32 v233, v232, v229
	s_waitcnt lgkmcnt(0)
	v_add_f32_e32 v229, v229, v233
	s_and_saveexec_b64 s[100:101], s[98:99]
	global_atomic_add_f32 v226, v229, s[16:17] offset:640
	s_mov_b64 exec, s[100:101]
	s_waitcnt vmcnt(21)
; __device__ __forceinline__ float bf_lo(unsigned w) { return __uint_as_float(w << 16); }
; __device__ __forceinline__ float bf_hi(unsigned w) { return __uint_as_float(w & 0xffff0000u); }
; __device__ __forceinline__ float sigmoidf_(float x) { return __builtin_amdgcn_rcpf(1.0f + __expf(-x)); }
; __device__ __forceinline__ float rinv_of(float ssq) { return rsqrtf(ssq * (1.0f / 1024.0f) + EPS); }
; __device__ __forceinline__ u32x4 pack8(const f32x4 a, const f32x4 b) { u32x4 w; w.x = cvt_pk_bf16(a[0], a[1]); w.y = cvt_pk_bf16(a[2], a[3]); w.z = cvt_pk_bf16(b[0], b[1]); w.w = cvt_pk_bf16(b[2], b[3]); return w; }
; __device__ __forceinline__ float sq8(const f32x4 a, const f32x4 b) { return (a[0] * a[0] + a[1] * a[1]) + (a[2] * a[2] + a[3] * a[3]) + (b[0] * b[0] + b[1] * b[1]) + (b[2] * b[2] + b[3] * b[3]); }
; __device__ __forceinline__ void ssq_commit(float s, float* ssq, int r, int fq) { s += __shfl_xor(s, 16); s += __shfl_xor(s, 32); if (fq == 0) atomicAdd(ssq + r, s); }
;     __device__ __forceinline__ void operator()(const AccT& acc, const pg8::Unit& u, int wr, int wc, int fr, int fq) const {
;     ...
;                 for (int mm = 0; mm < 2; ++mm) { const int m = 2 * mp + mm, r = EPI_ROW(u, ai, m); float s = 0.f; const float ri = rinv_of(rs[mm]);
; #pragma unroll
;                     for (int bj = 0; bj < 2; ++bj) { const int c = EPI_COL(u, bj); float* hp = h + (size_t)r * D + c; const u32x4 p4 = pw[mm][bj];
;                         const f32x4 a0 = acc[ai][bj][m][0] * ri, a1 = acc[ai][bj][m][1] * ri; f32x4 v0 = hv[mm][bj][0], v1 = hv[mm][bj][1];
;                         v0[0] += mul * sigmoidf_(a0[0]) * bf_lo(p4.x); v0[1] += mul * sigmoidf_(a0[1]) * bf_hi(p4.x); v0[2] += mul * sigmoidf_(a0[2]) * bf_lo(p4.y); v0[3] += mul * sigmoidf_(a0[3]) * bf_hi(p4.y);
;                         v1[0] += mul * sigmoidf_(a1[0]) * bf_lo(p4.z); v1[1] += mul * sigmoidf_(a1[1]) * bf_hi(p4.z); v1[2] += mul * sigmoidf_(a1[2]) * bf_lo(p4.w); v1[3] += mul * sigmoidf_(a1[3]) * bf_hi(p4.w);
;                         *(f32x4*)hp = v0; *(f32x4*)(hp + 4) = v1;
;                         if (hb) *(u32x4*)(hb + (size_t)r * D + c) = pack8(v0, v1);
;                         s += sq8(v0, v1); }
;                     ssq_commit(s, ssq, r, fq); }
	v_fmamk_f32 v230, v228, 0x3a800000, v225
	v_rsq_f32_e32 v230, v230
	v_mov_b32_e32 v229, 0
	v_pk_mul_f32 v[236:237], v[12:13], v[230:231] op_sel_hi:[1,0]
	v_pk_mul_f32 v[238:239], v[14:15], v[230:231] op_sel_hi:[1,0]
	v_mul_f32_e32 v236, 0xbfb8aa3b, v236
	v_mul_f32_e32 v237, 0xbfb8aa3b, v237
	v_mul_f32_e32 v238, 0xbfb8aa3b, v238
	v_mul_f32_e32 v239, 0xbfb8aa3b, v239
	v_exp_f32_e32 v236, v236
	v_exp_f32_e32 v237, v237
	v_exp_f32_e32 v238, v238
	v_exp_f32_e32 v239, v239
	v_add_f32_e32 v236, 1.0, v236
	v_add_f32_e32 v237, 1.0, v237
	v_add_f32_e32 v238, 1.0, v238
	v_add_f32_e32 v239, 1.0, v239
	v_rcp_f32_e32 v236, v236
	v_rcp_f32_e32 v237, v237
	v_rcp_f32_e32 v238, v238
	v_rcp_f32_e32 v239, v239
	v_lshlrev_b32_e32 v232, 16, v220
	v_and_b32_e32 v233, 0xffff0000, v220
	v_lshlrev_b32_e32 v234, 16, v221
	v_and_b32_e32 v235, 0xffff0000, v221
	v_pk_fma_f32 v[12:13], v[236:237], v[232:233], v[194:195]
	v_pk_fma_f32 v[14:15], v[238:239], v[234:235], v[196:197]
	v_pk_mul_f32 v[236:237], v[12:13], v[12:13]
	v_pk_mul_f32 v[238:239], v[14:15], v[14:15]
	v_add_f32_e32 v229, v229, v236
	v_add_f32_e32 v229, v229, v237
	v_add_f32_e32 v229, v229, v238
	v_add_f32_e32 v229, v229, v239
	v_pk_mul_f32 v[236:237], v[8:9], v[230:231] op_sel_hi:[1,0]
	v_pk_mul_f32 v[238:239], v[10:11], v[230:231] op_sel_hi:[1,0]
	v_mul_f32_e32 v236, 0xbfb8aa3b, v236
	v_mul_f32_e32 v237, 0xbfb8aa3b, v237
	v_mul_f32_e32 v238, 0xbfb8aa3b, v238
	v_mul_f32_e32 v239, 0xbfb8aa3b, v239
	v_exp_f32_e32 v236, v236
	v_exp_f32_e32 v237, v237
	v_exp_f32_e32 v238, v238
	v_exp_f32_e32 v239, v239
	v_add_f32_e32 v236, 1.0, v236
	v_add_f32_e32 v237, 1.0, v237
	v_add_f32_e32 v238, 1.0, v238
	v_add_f32_e32 v239, 1.0, v239
	v_rcp_f32_e32 v236, v236
	v_rcp_f32_e32 v237, v237
	v_rcp_f32_e32 v238, v238
	v_rcp_f32_e32 v239, v239
	v_lshlrev_b32_e32 v232, 16, v222
	v_and_b32_e32 v233, 0xffff0000, v222
	v_lshlrev_b32_e32 v234, 16, v223
	v_and_b32_e32 v235, 0xffff0000, v223
	v_pk_fma_f32 v[8:9], v[236:237], v[232:233], v[198:199]
	v_pk_fma_f32 v[10:11], v[238:239], v[234:235], v[200:201]
	v_pk_mul_f32 v[236:237], v[8:9], v[8:9]
	v_pk_mul_f32 v[238:239], v[10:11], v[10:11]
	v_add_f32_e32 v229, v229, v236
	v_add_f32_e32 v229, v229, v237
	v_add_f32_e32 v229, v229, v238
	v_add_f32_e32 v229, v229, v239
	v_pk_mul_f32 v[236:237], v[4:5], v[230:231] op_sel_hi:[1,0]
	v_pk_mul_f32 v[238:239], v[6:7], v[230:231] op_sel_hi:[1,0]
	v_mul_f32_e32 v236, 0xbfb8aa3b, v236
	v_mul_f32_e32 v237, 0xbfb8aa3b, v237
	v_mul_f32_e32 v238, 0xbfb8aa3b, v238
	v_mul_f32_e32 v239, 0xbfb8aa3b, v239
	v_exp_f32_e32 v236, v236
	v_exp_f32_e32 v237, v237
	v_exp_f32_e32 v238, v238
	v_exp_f32_e32 v239, v239
	v_add_f32_e32 v236, 1.0, v236
	v_add_f32_e32 v237, 1.0, v237
	v_add_f32_e32 v238, 1.0, v238
	v_add_f32_e32 v239, 1.0, v239
	v_rcp_f32_e32 v236, v236
	v_rcp_f32_e32 v237, v237
	v_rcp_f32_e32 v238, v238
	v_rcp_f32_e32 v239, v239
	v_lshlrev_b32_e32 v232, 16, v244
	v_and_b32_e32 v233, 0xffff0000, v244
	v_lshlrev_b32_e32 v234, 16, v245
	v_and_b32_e32 v235, 0xffff0000, v245
	v_pk_fma_f32 v[4:5], v[236:237], v[232:233], v[202:203]
	v_pk_fma_f32 v[6:7], v[238:239], v[234:235], v[204:205]
	v_pk_mul_f32 v[236:237], v[4:5], v[4:5]
	v_pk_mul_f32 v[238:239], v[6:7], v[6:7]
	v_add_f32_e32 v229, v229, v236
	v_add_f32_e32 v229, v229, v237
	v_add_f32_e32 v229, v229, v238
	v_add_f32_e32 v229, v229, v239
	v_pk_mul_f32 v[236:237], v[0:1], v[230:231] op_sel_hi:[1,0]
	v_pk_mul_f32 v[238:239], v[2:3], v[230:231] op_sel_hi:[1,0]
	v_mul_f32_e32 v236, 0xbfb8aa3b, v236
	v_mul_f32_e32 v237, 0xbfb8aa3b, v237
	v_mul_f32_e32 v238, 0xbfb8aa3b, v238
	v_mul_f32_e32 v239, 0xbfb8aa3b, v239
	v_exp_f32_e32 v236, v236
	v_exp_f32_e32 v237, v237
	v_exp_f32_e32 v238, v238
	v_exp_f32_e32 v239, v239
	v_add_f32_e32 v236, 1.0, v236
	v_add_f32_e32 v237, 1.0, v237
	v_add_f32_e32 v238, 1.0, v238
	v_add_f32_e32 v239, 1.0, v239
	v_rcp_f32_e32 v236, v236
	v_rcp_f32_e32 v237, v237
	v_rcp_f32_e32 v238, v238
	v_rcp_f32_e32 v239, v239
	v_lshlrev_b32_e32 v232, 16, v246
	v_and_b32_e32 v233, 0xffff0000, v246
	v_lshlrev_b32_e32 v234, 16, v247
	v_and_b32_e32 v235, 0xffff0000, v247
	v_pk_fma_f32 v[0:1], v[236:237], v[232:233], v[206:207]
	v_pk_fma_f32 v[2:3], v[238:239], v[234:235], v[208:209]
	v_pk_mul_f32 v[236:237], v[0:1], v[0:1]
	v_pk_mul_f32 v[238:239], v[2:3], v[2:3]
	v_add_f32_e32 v229, v229, v236
	v_add_f32_e32 v229, v229, v237
	v_add_f32_e32 v229, v229, v238
	v_add_f32_e32 v229, v229, v239
	v_add_u32_e32 v232, 0xb0000, v243
	v_lshrrev_b32_e32 v233, 1, v232
	v_cvt_pk_bf16_f32 v220, v12, v13
	v_cvt_pk_bf16_f32 v221, v14, v15
	v_cvt_pk_bf16_f32 v222, v8, v9
	v_cvt_pk_bf16_f32 v223, v10, v11
	v_cvt_pk_bf16_f32 v244, v4, v5
	v_cvt_pk_bf16_f32 v245, v6, v7
	v_cvt_pk_bf16_f32 v246, v0, v1
	v_cvt_pk_bf16_f32 v247, v2, v3
	global_store_dwordx4 v232, v[12:15], s[52:53]
	global_store_dwordx4 v232, v[8:11], s[52:53] offset:16
	global_store_dwordx4 v232, v[4:7], s[52:53] offset:512
	global_store_dwordx4 v232, v[0:3], s[52:53] offset:528
	global_store_dwordx4 v233, v[220:223], s[70:71]
	global_store_dwordx4 v233, v[244:247], s[70:71] offset:256
	v_xor_b32_e32 v232, 64, v224
	ds_bpermute_b32 v233, v232, v229
	s_waitcnt lgkmcnt(0)
	v_add_f32_e32 v229, v229, v233
	v_xor_b32_e32 v232, 0x80, v224
	ds_bpermute_b32 v233, v232, v229
	s_waitcnt lgkmcnt(0)
	v_add_f32_e32 v229, v229, v233
	s_and_saveexec_b64 s[100:101], s[98:99]
	global_atomic_add_f32 v226, v229, s[16:17] offset:704
	s_mov_b64 exec, s[100:101]
	s_mov_b64 s[12:13], exec
	s_branch .LBB0_1744
